# per-segment s_setprio pairs removed from the four GEMM main loops
# speedup vs baseline: 1.0083x; 1.0060x over previous
; #define PG8_STAGE(bufoff, gbase, voff) do { _Pragma("unroll") for (int _i = 0; _i < 2; ++_i) \
;         __builtin_amdgcn_global_load_lds((const unsigned*)((const char*)(gbase) + (voff)[_i]), (LAS unsigned*)(lds + (bufoff) + ldsw + _i * 8192), 16, 0, 0); } while (0)
; #define PG8_LDA(dst, b, h) do { _Pragma("unroll") for (int m = 0; m < 4; ++m) _Pragma("unroll") for (int k = 0; k < 2; ++k) dst[m][k] = *(const LAS bf16x8*)(lds + PG8_SA(b, h) + aoff + m * 2048 + k * 1024); } while (0)
; #define PG8_LDB(dst, b, h) do { _Pragma("unroll") for (int n = 0; n < 2; ++n) _Pragma("unroll") for (int k = 0; k < 2; ++k) dst[n][k] = *(const LAS bf16x8*)(lds + PG8_SB(b, h) + boff + n * 2048 + k * 1024); } while (0)
; #define PG8_MMA(ai, bj, At, Bt) do { __builtin_amdgcn_s_setprio(1); _Pragma("unroll") for (int m = 0; m < 4; ++m) _Pragma("unroll") for (int n = 0; n < 2; ++n) _Pragma("unroll") for (int k = 0; k < 2; ++k) \
;         acc[ai][bj][m][n] = __builtin_amdgcn_mfma_f32_16x16x32_bf16(Bt[n][k], At[m][k], acc[ai][bj][m][n], 0, 0, 0); __builtin_amdgcn_s_setprio(0); } while (0)
; #define PG8_WAIT_V(n) asm volatile("s_waitcnt vmcnt(" #n ")" ::: "memory")
; #define PG8_WAIT_L(n) asm volatile("s_waitcnt lgkmcnt(" #n ")" ::: "memory")
; #define PG8_BAR __builtin_amdgcn_s_barrier()
; #define PG8_SCHED __builtin_amdgcn_sched_barrier(0)
; template <class Epi, class Sched>
; __device__ __forceinline__ void gemm_phase(LAS unsigned char* lds, const Gemm g, const Sched& S, const Epi& E) {
;     ...
;             PG8_LDB(B0, 0, 0); PG8_LDB(B1, 0, 1); PG8_SCHED; PG8_LDA(At, 0, 0); PG8_STAGE(PG8_SA(1, 1), a1 + hstepA, voffA);
;             PG8_WAIT_V(8); PG8_WAIT_L(0); PG8_BAR; PG8_MMA(0, 0, At, B0); PG8_MMA(0, 1, At, B1); PG8_BAR; PG8_SCHED;
;             PG8_LDA(At, 0, 1); PG8_STAGE(PG8_SB(0, 0), b2, voffB); PG8_STAGE(PG8_SB(0, 1), b2 + hstepB, voffB); PG8_STAGE(PG8_SA(0, 0), a2, voffA);
;             PG8_WAIT_V(8); PG8_WAIT_L(0); PG8_BAR; PG8_MMA(1, 0, At, B0); PG8_MMA(1, 1, At, B1); PG8_BAR; PG8_SCHED;
.LBB0_178:
	ds_read_b128 v[148:151], v163
	ds_read_b128 v[152:155], v163 offset:1024
	ds_read_b128 v[156:159], v163 offset:2048
	ds_read_b128 v[168:171], v163 offset:3072
	ds_read_b128 v[172:175], v164
	ds_read_b128 v[176:179], v164 offset:1024
	ds_read_b128 v[180:183], v164 offset:2048
	ds_read_b128 v[184:187], v164 offset:3072
	s_add_u32 s2, s8, 0xfff80080
	s_addc_u32 s12, s9, -1
	s_cmp_eq_u32 s43, 28
	s_cselect_b32 s41, s7, s12
	s_cselect_b32 s40, s11, s2
	s_cselect_b32 s13, s31, s42
	s_cselect_b32 s12, s33, s35
	v_lshl_add_u64 v[222:223], s[8:9], 0, v[140:141]
	s_add_i32 m0, s53, 0xc000
	ds_read_b128 v[188:191], v165
	ds_read_b128 v[192:195], v165 offset:1024
	ds_read_b128 v[196:199], v165 offset:2048
	ds_read_b128 v[200:203], v165 offset:3072
	ds_read_b128 v[204:207], v165 offset:4096
	ds_read_b128 v[210:213], v165 offset:5120
	ds_read_b128 v[214:217], v165 offset:6144
	ds_read_b128 v[218:221], v165 offset:7168
	global_load_lds_dwordx4 v[222:223], off
	v_lshl_add_u64 v[222:223], s[8:9], 0, v[142:143]
	s_add_i32 m0, s53, 0xe000
	s_nop 0
	global_load_lds_dwordx4 v[222:223], off
	global_load_dwordx2 v[232:233], v240, s[98:99] nt
	s_add_u32 s98, s98, s100
	s_addc_u32 s99, s99, 0
	global_load_dwordx2 v[234:235], v240, s[98:99] nt
	s_add_u32 s98, s98, s100
	s_addc_u32 s99, s99, 0
	global_load_dwordx2 v[236:237], v240, s[98:99] nt
	s_add_u32 s98, s98, s100
	s_addc_u32 s99, s99, 0
	global_load_dwordx2 v[238:239], v240, s[98:99] nt
	s_add_u32 s98, s98, s100
	s_addc_u32 s99, s99, 0
	global_load_dwordx2 a[0:1], v240, s[98:99] nt
	s_add_u32 s98, s98, s100
	s_addc_u32 s99, s99, 0
	global_load_dwordx2 a[2:3], v240, s[98:99] nt
	s_add_u32 s98, s98, s100
	s_addc_u32 s99, s99, 0
	global_load_dwordx2 a[4:5], v240, s[98:99] nt
	s_add_u32 s98, s98, s100
	s_addc_u32 s99, s99, 0
	global_load_dwordx2 a[6:7], v240, s[98:99] nt
	s_add_u32 s98, s98, s100
	s_addc_u32 s99, s99, 0
	s_waitcnt vmcnt(16)
	s_waitcnt lgkmcnt(0)
	s_barrier
	s_waitcnt lgkmcnt(0)
	v_mfma_f32_16x16x32_bf16 v[124:127], v[148:151], v[188:191], v[124:127]
	v_mfma_f32_16x16x32_bf16 v[120:123], v[156:159], v[188:191], v[120:123]
	v_mfma_f32_16x16x32_bf16 v[116:119], v[148:151], v[196:199], v[116:119]
	v_mfma_f32_16x16x32_bf16 v[112:115], v[156:159], v[196:199], v[112:115]
	v_mfma_f32_16x16x32_bf16 v[108:111], v[148:151], v[204:207], v[108:111]
	v_mfma_f32_16x16x32_bf16 v[104:107], v[156:159], v[204:207], v[104:107]
	v_mfma_f32_16x16x32_bf16 v[100:103], v[148:151], v[214:217], v[100:103]
	v_mfma_f32_16x16x32_bf16 v[96:99], v[156:159], v[214:217], v[96:99]
	v_mfma_f32_16x16x32_bf16 v[124:127], v[152:155], v[192:195], v[124:127]
	v_mfma_f32_16x16x32_bf16 v[120:123], v[168:171], v[192:195], v[120:123]
	v_mfma_f32_16x16x32_bf16 v[116:119], v[152:155], v[200:203], v[116:119]
	v_mfma_f32_16x16x32_bf16 v[112:115], v[168:171], v[200:203], v[112:115]
	v_mfma_f32_16x16x32_bf16 v[108:111], v[152:155], v[210:213], v[108:111]
	v_mfma_f32_16x16x32_bf16 v[104:107], v[168:171], v[210:213], v[104:107]
	v_mfma_f32_16x16x32_bf16 v[100:103], v[152:155], v[218:221], v[100:103]
	v_mfma_f32_16x16x32_bf16 v[96:99], v[168:171], v[218:221], v[96:99]
	v_mfma_f32_16x16x32_bf16 v[60:63], v[172:175], v[188:191], v[60:63]
	v_mfma_f32_16x16x32_bf16 v[56:59], v[180:183], v[188:191], v[56:59]
	v_mfma_f32_16x16x32_bf16 v[52:55], v[172:175], v[196:199], v[52:55]
	v_mfma_f32_16x16x32_bf16 v[48:51], v[180:183], v[196:199], v[48:51]
	v_mfma_f32_16x16x32_bf16 v[44:47], v[172:175], v[204:207], v[44:47]
	v_mfma_f32_16x16x32_bf16 v[40:43], v[180:183], v[204:207], v[40:43]
	v_mfma_f32_16x16x32_bf16 v[36:39], v[172:175], v[214:217], v[36:39]
	v_mfma_f32_16x16x32_bf16 v[32:35], v[180:183], v[214:217], v[32:35]
	v_mfma_f32_16x16x32_bf16 v[60:63], v[176:179], v[192:195], v[60:63]
	v_mfma_f32_16x16x32_bf16 v[56:59], v[184:187], v[192:195], v[56:59]
	v_mfma_f32_16x16x32_bf16 v[52:55], v[176:179], v[200:203], v[52:55]
	v_mfma_f32_16x16x32_bf16 v[48:51], v[184:187], v[200:203], v[48:51]
	v_mfma_f32_16x16x32_bf16 v[44:47], v[176:179], v[210:213], v[44:47]
	v_mfma_f32_16x16x32_bf16 v[40:43], v[184:187], v[210:213], v[40:43]
	v_mfma_f32_16x16x32_bf16 v[36:39], v[176:179], v[218:221], v[36:39]
	v_mfma_f32_16x16x32_bf16 v[32:35], v[184:187], v[218:221], v[32:35]
	s_barrier
	s_add_i32 s2, s64, s52
	v_lshl_add_u64 v[222:223], s[12:13], 0, v[130:131]
	s_mov_b32 m0, s2
	ds_read_b128 v[188:191], v165 offset:16384
	ds_read_b128 v[192:195], v165 offset:17408
	ds_read_b128 v[196:199], v165 offset:18432
	ds_read_b128 v[200:203], v165 offset:19456
	ds_read_b128 v[204:207], v165 offset:20480
	ds_read_b128 v[210:213], v165 offset:21504
	ds_read_b128 v[214:217], v165 offset:22528
	ds_read_b128 v[218:221], v165 offset:23552
	global_load_lds_dwordx4 v[222:223], off
	s_add_i32 m0, s2, 0x2000
	s_add_u32 s44, s12, 0x80000
	v_lshl_add_u64 v[224:225], s[12:13], 0, v[134:135]
	s_addc_u32 s45, s13, 0
	s_add_i32 s2, s65, s52
	global_load_lds_dwordx4 v[224:225], off
	v_lshl_add_u64 v[226:227], s[44:45], 0, v[130:131]
	s_mov_b32 m0, s2
	v_lshl_add_u64 v[228:229], s[40:41], 0, v[132:133]
	global_load_lds_dwordx4 v[226:227], off
	v_lshl_add_u64 v[226:227], s[44:45], 0, v[134:135]
	s_add_i32 m0, s2, 0x2000
	s_nop 0
	global_load_lds_dwordx4 v[226:227], off
	v_lshl_add_u64 v[226:227], s[40:41], 0, v[128:129]
	s_mov_b32 m0, s53
	s_nop 0
	global_load_lds_dwordx4 v[226:227], off
	s_mov_b32 m0, s54
	s_nop 0
	global_load_lds_dwordx4 v[228:229], off
	s_waitcnt vmcnt(16)
	s_waitcnt lgkmcnt(0)
	s_barrier
; #define PG8_STAGE(bufoff, gbase, voff) do { _Pragma("unroll") for (int _i = 0; _i < 2; ++_i) \
;         __builtin_amdgcn_global_load_lds((const unsigned*)((const char*)(gbase) + (voff)[_i]), (LAS unsigned*)(lds + (bufoff) + ldsw + _i * 8192), 16, 0, 0); } while (0)
; #define PG8_LDA(dst, b, h) do { _Pragma("unroll") for (int m = 0; m < 4; ++m) _Pragma("unroll") for (int k = 0; k < 2; ++k) dst[m][k] = *(const LAS bf16x8*)(lds + PG8_SA(b, h) + aoff + m * 2048 + k * 1024); } while (0)
; #define PG8_LDB(dst, b, h) do { _Pragma("unroll") for (int n = 0; n < 2; ++n) _Pragma("unroll") for (int k = 0; k < 2; ++k) dst[n][k] = *(const LAS bf16x8*)(lds + PG8_SB(b, h) + boff + n * 2048 + k * 1024); } while (0)
; #define PG8_MMA(ai, bj, At, Bt) do { __builtin_amdgcn_s_setprio(1); _Pragma("unroll") for (int m = 0; m < 4; ++m) _Pragma("unroll") for (int n = 0; n < 2; ++n) _Pragma("unroll") for (int k = 0; k < 2; ++k) \
;         acc[ai][bj][m][n] = __builtin_amdgcn_mfma_f32_16x16x32_bf16(Bt[n][k], At[m][k], acc[ai][bj][m][n], 0, 0, 0); __builtin_amdgcn_s_setprio(0); } while (0)
; #define PG8_WAIT_V(n) asm volatile("s_waitcnt vmcnt(" #n ")" ::: "memory")
; #define PG8_WAIT_L(n) asm volatile("s_waitcnt lgkmcnt(" #n ")" ::: "memory")
; #define PG8_BAR __builtin_amdgcn_s_barrier()
; #define PG8_SCHED __builtin_amdgcn_sched_barrier(0)
; template <class Epi, class Sched>
; __device__ __forceinline__ void gemm_phase(LAS unsigned char* lds, const Gemm g, const Sched& S, const Epi& E) {
;     ...
;             PG8_WAIT_V(8); PG8_WAIT_L(0); PG8_BAR; PG8_MMA(1, 0, At, B0); PG8_MMA(1, 1, At, B1); PG8_BAR; PG8_SCHED;
;             PG8_LDB(B0, 1, 0); PG8_LDB(B1, 1, 1); PG8_SCHED; PG8_LDA(At, 1, 0); PG8_STAGE(PG8_SA(0, 1), a2 + hstepA, voffA);
;             PG8_WAIT_V(8); PG8_WAIT_L(0); PG8_BAR; PG8_MMA(0, 0, At, B0); PG8_MMA(0, 1, At, B1); PG8_BAR; PG8_SCHED;
;             PG8_LDA(At, 1, 1); PG8_STAGE(PG8_SB(1, 0), b3, voffB); PG8_STAGE(PG8_SB(1, 1), b3 + hstepB, voffB); PG8_STAGE(PG8_SA(1, 0), a3, voffA);
	s_waitcnt lgkmcnt(0)
	v_mfma_f32_16x16x32_bf16 v[92:95], v[148:151], v[188:191], v[92:95]
	v_mfma_f32_16x16x32_bf16 v[88:91], v[156:159], v[188:191], v[88:91]
	v_mfma_f32_16x16x32_bf16 v[84:87], v[148:151], v[196:199], v[84:87]
	v_mfma_f32_16x16x32_bf16 v[80:83], v[156:159], v[196:199], v[80:83]
	v_mfma_f32_16x16x32_bf16 v[76:79], v[148:151], v[204:207], v[76:79]
	v_mfma_f32_16x16x32_bf16 v[72:75], v[156:159], v[204:207], v[72:75]
	v_mfma_f32_16x16x32_bf16 v[68:71], v[148:151], v[214:217], v[68:71]
	v_mfma_f32_16x16x32_bf16 v[64:67], v[156:159], v[214:217], v[64:67]
	v_mfma_f32_16x16x32_bf16 v[92:95], v[152:155], v[192:195], v[92:95]
	v_mfma_f32_16x16x32_bf16 v[88:91], v[168:171], v[192:195], v[88:91]
	v_mfma_f32_16x16x32_bf16 v[84:87], v[152:155], v[200:203], v[84:87]
	v_mfma_f32_16x16x32_bf16 v[80:83], v[168:171], v[200:203], v[80:83]
	v_mfma_f32_16x16x32_bf16 v[76:79], v[152:155], v[210:213], v[76:79]
	v_mfma_f32_16x16x32_bf16 v[72:75], v[168:171], v[210:213], v[72:75]
	v_mfma_f32_16x16x32_bf16 v[68:71], v[152:155], v[218:221], v[68:71]
	v_mfma_f32_16x16x32_bf16 v[64:67], v[168:171], v[218:221], v[64:67]
	v_mfma_f32_16x16x32_bf16 v[28:31], v[172:175], v[188:191], v[28:31]
	v_mfma_f32_16x16x32_bf16 v[24:27], v[180:183], v[188:191], v[24:27]
	v_mfma_f32_16x16x32_bf16 v[20:23], v[172:175], v[196:199], v[20:23]
	v_mfma_f32_16x16x32_bf16 v[16:19], v[180:183], v[196:199], v[16:19]
	v_mfma_f32_16x16x32_bf16 v[12:15], v[172:175], v[204:207], v[12:15]
	v_mfma_f32_16x16x32_bf16 v[8:11], v[180:183], v[204:207], v[8:11]
	v_mfma_f32_16x16x32_bf16 v[4:7], v[172:175], v[214:217], v[4:7]
	v_mfma_f32_16x16x32_bf16 v[0:3], v[180:183], v[214:217], v[0:3]
	v_mfma_f32_16x16x32_bf16 v[28:31], v[176:179], v[192:195], v[28:31]
	v_mfma_f32_16x16x32_bf16 v[24:27], v[184:187], v[192:195], v[24:27]
	v_mfma_f32_16x16x32_bf16 v[20:23], v[176:179], v[200:203], v[20:23]
	v_mfma_f32_16x16x32_bf16 v[16:19], v[184:187], v[200:203], v[16:19]
	v_mfma_f32_16x16x32_bf16 v[12:15], v[176:179], v[210:213], v[12:15]
	v_mfma_f32_16x16x32_bf16 v[8:11], v[184:187], v[210:213], v[8:11]
	v_mfma_f32_16x16x32_bf16 v[4:7], v[176:179], v[218:221], v[4:7]
	v_mfma_f32_16x16x32_bf16 v[0:3], v[184:187], v[218:221], v[0:3]
	s_barrier
	s_add_i32 s2, 0, 0x18000
	v_add_u32_e32 v136, s2, v161
	s_add_i32 s44, 0, 0x1c000
	ds_read_b128 v[148:151], v136
	ds_read_b128 v[152:155], v136 offset:1024
	ds_read_b128 v[156:159], v136 offset:2048
	ds_read_b128 v[168:171], v136 offset:3072
	v_add_u32_e32 v136, s44, v161
	ds_read_b128 v[172:175], v136
	ds_read_b128 v[176:179], v136 offset:1024
	ds_read_b128 v[180:183], v136 offset:2048
	ds_read_b128 v[184:187], v136 offset:3072
	s_add_u32 s40, s40, 0x80000
	s_addc_u32 s41, s41, 0
	s_mov_b32 m0, s55
	v_lshl_add_u64 v[230:231], s[40:41], 0, v[128:129]
	ds_read_b128 v[188:191], v165 offset:32768
	ds_read_b128 v[192:195], v165 offset:33792
	ds_read_b128 v[196:199], v165 offset:34816
	ds_read_b128 v[200:203], v165 offset:35840
	ds_read_b128 v[204:207], v165 offset:36864
	ds_read_b128 v[210:213], v165 offset:37888
	ds_read_b128 v[214:217], v165 offset:38912
	ds_read_b128 v[218:221], v165 offset:39936
	global_load_lds_dwordx4 v[230:231], off
	v_lshl_add_u64 v[230:231], s[40:41], 0, v[132:133]
	s_mov_b32 m0, s56
	s_nop 0
	global_load_lds_dwordx4 v[230:231], off
	s_waitcnt vmcnt(16)
	s_waitcnt lgkmcnt(0)
	s_barrier
	s_waitcnt lgkmcnt(0)
	v_mfma_f32_16x16x32_bf16 v[124:127], v[148:151], v[188:191], v[124:127]
	v_mfma_f32_16x16x32_bf16 v[120:123], v[156:159], v[188:191], v[120:123]
	v_mfma_f32_16x16x32_bf16 v[116:119], v[148:151], v[196:199], v[116:119]
	v_mfma_f32_16x16x32_bf16 v[112:115], v[156:159], v[196:199], v[112:115]
	v_mfma_f32_16x16x32_bf16 v[108:111], v[148:151], v[204:207], v[108:111]
	v_mfma_f32_16x16x32_bf16 v[104:107], v[156:159], v[204:207], v[104:107]
	v_mfma_f32_16x16x32_bf16 v[100:103], v[148:151], v[214:217], v[100:103]
	v_mfma_f32_16x16x32_bf16 v[96:99], v[156:159], v[214:217], v[96:99]
	v_mfma_f32_16x16x32_bf16 v[124:127], v[152:155], v[192:195], v[124:127]
	v_mfma_f32_16x16x32_bf16 v[120:123], v[168:171], v[192:195], v[120:123]
	v_mfma_f32_16x16x32_bf16 v[116:119], v[152:155], v[200:203], v[116:119]
	v_mfma_f32_16x16x32_bf16 v[112:115], v[168:171], v[200:203], v[112:115]
	v_mfma_f32_16x16x32_bf16 v[108:111], v[152:155], v[210:213], v[108:111]
	v_mfma_f32_16x16x32_bf16 v[104:107], v[168:171], v[210:213], v[104:107]
	v_mfma_f32_16x16x32_bf16 v[100:103], v[152:155], v[218:221], v[100:103]
	v_mfma_f32_16x16x32_bf16 v[96:99], v[168:171], v[218:221], v[96:99]
	v_mfma_f32_16x16x32_bf16 v[60:63], v[172:175], v[188:191], v[60:63]
	v_mfma_f32_16x16x32_bf16 v[56:59], v[180:183], v[188:191], v[56:59]
	v_mfma_f32_16x16x32_bf16 v[52:55], v[172:175], v[196:199], v[52:55]
	v_mfma_f32_16x16x32_bf16 v[48:51], v[180:183], v[196:199], v[48:51]
	v_mfma_f32_16x16x32_bf16 v[44:47], v[172:175], v[204:207], v[44:47]
	v_mfma_f32_16x16x32_bf16 v[40:43], v[180:183], v[204:207], v[40:43]
	v_mfma_f32_16x16x32_bf16 v[36:39], v[172:175], v[214:217], v[36:39]
	v_mfma_f32_16x16x32_bf16 v[32:35], v[180:183], v[214:217], v[32:35]
	v_mfma_f32_16x16x32_bf16 v[60:63], v[176:179], v[192:195], v[60:63]
	v_mfma_f32_16x16x32_bf16 v[56:59], v[184:187], v[192:195], v[56:59]
	v_mfma_f32_16x16x32_bf16 v[52:55], v[176:179], v[200:203], v[52:55]
	v_mfma_f32_16x16x32_bf16 v[48:51], v[184:187], v[200:203], v[48:51]
	v_mfma_f32_16x16x32_bf16 v[44:47], v[176:179], v[210:213], v[44:47]
	v_mfma_f32_16x16x32_bf16 v[40:43], v[184:187], v[210:213], v[40:43]
	v_mfma_f32_16x16x32_bf16 v[36:39], v[176:179], v[218:221], v[36:39]
	v_mfma_f32_16x16x32_bf16 v[32:35], v[184:187], v[218:221], v[32:35]
	s_barrier
; #define PG8_STAGE(bufoff, gbase, voff) do { _Pragma("unroll") for (int _i = 0; _i < 2; ++_i) \
;         __builtin_amdgcn_global_load_lds((const unsigned*)((const char*)(gbase) + (voff)[_i]), (LAS unsigned*)(lds + (bufoff) + ldsw + _i * 8192), 16, 0, 0); } while (0)
; #define PG8_LDA(dst, b, h) do { _Pragma("unroll") for (int m = 0; m < 4; ++m) _Pragma("unroll") for (int k = 0; k < 2; ++k) dst[m][k] = *(const LAS bf16x8*)(lds + PG8_SA(b, h) + aoff + m * 2048 + k * 1024); } while (0)
; #define PG8_MMA(ai, bj, At, Bt) do { __builtin_amdgcn_s_setprio(1); _Pragma("unroll") for (int m = 0; m < 4; ++m) _Pragma("unroll") for (int n = 0; n < 2; ++n) _Pragma("unroll") for (int k = 0; k < 2; ++k) \
;         acc[ai][bj][m][n] = __builtin_amdgcn_mfma_f32_16x16x32_bf16(Bt[n][k], At[m][k], acc[ai][bj][m][n], 0, 0, 0); __builtin_amdgcn_s_setprio(0); } while (0)
; #define PG8_WAIT_V(n) asm volatile("s_waitcnt vmcnt(" #n ")" ::: "memory")
; #define PG8_WAIT_L(n) asm volatile("s_waitcnt lgkmcnt(" #n ")" ::: "memory")
; #define PG8_BAR __builtin_amdgcn_s_barrier()
; #define PG8_SCHED __builtin_amdgcn_sched_barrier(0)
; template <class Epi, class Sched>
; __device__ __forceinline__ void gemm_phase(LAS unsigned char* lds, const Gemm g, const Sched& S, const Epi& E) {
;     ...
;             PG8_LDA(At, 1, 1); PG8_STAGE(PG8_SB(1, 0), b3, voffB); PG8_STAGE(PG8_SB(1, 1), b3 + hstepB, voffB); PG8_STAGE(PG8_SA(1, 0), a3, voffA);
;             PG8_WAIT_V(8); PG8_WAIT_L(0); PG8_BAR; PG8_MMA(1, 0, At, B0); PG8_MMA(1, 1, At, B1); PG8_BAR; PG8_SCHED;
	s_add_i32 s2, s2, s52
	v_lshl_add_u64 v[222:223], v[222:223], 0, s[18:19]
	s_mov_b32 m0, s2
	ds_read_b128 v[188:191], v165 offset:49152
	ds_read_b128 v[192:195], v165 offset:50176
	ds_read_b128 v[196:199], v165 offset:51200
	ds_read_b128 v[200:203], v165 offset:52224
	ds_read_b128 v[204:207], v165 offset:53248
	ds_read_b128 v[210:213], v165 offset:54272
	ds_read_b128 v[214:217], v165 offset:55296
	ds_read_b128 v[218:221], v165 offset:56320
	global_load_lds_dwordx4 v[222:223], off
	s_add_i32 m0, s2, 0x2000
	s_add_u32 s12, s12, 0x80080
	v_lshl_add_u64 v[222:223], v[224:225], 0, s[18:19]
	s_addc_u32 s13, s13, 0
	s_add_i32 s2, s44, s52
	global_load_lds_dwordx4 v[222:223], off
	v_lshl_add_u64 v[222:223], s[12:13], 0, v[130:131]
	s_mov_b32 m0, s2
	s_nop 0
	global_load_lds_dwordx4 v[222:223], off
	v_lshl_add_u64 v[222:223], s[12:13], 0, v[134:135]
	s_add_i32 m0, s2, 0x2000
	s_nop 0
	global_load_lds_dwordx4 v[222:223], off
	v_lshl_add_u64 v[222:223], v[226:227], 0, s[18:19]
	s_mov_b32 m0, s58
	s_nop 0
	global_load_lds_dwordx4 v[222:223], off
	v_lshl_add_u64 v[222:223], v[228:229], 0, s[18:19]
	s_mov_b32 m0, s59
	s_nop 0
	global_load_lds_dwordx4 v[222:223], off
	s_waitcnt vmcnt(8)
	s_waitcnt lgkmcnt(0)
	s_barrier
	s_waitcnt lgkmcnt(0)
	v_mfma_f32_16x16x32_bf16 v[92:95], v[148:151], v[188:191], v[92:95]
	v_mfma_f32_16x16x32_bf16 v[88:91], v[156:159], v[188:191], v[88:91]
	v_mfma_f32_16x16x32_bf16 v[84:87], v[148:151], v[196:199], v[84:87]
	v_mfma_f32_16x16x32_bf16 v[80:83], v[156:159], v[196:199], v[80:83]
	v_mfma_f32_16x16x32_bf16 v[76:79], v[148:151], v[204:207], v[76:79]
	v_mfma_f32_16x16x32_bf16 v[72:75], v[156:159], v[204:207], v[72:75]
	v_mfma_f32_16x16x32_bf16 v[68:71], v[148:151], v[214:217], v[68:71]
	v_mfma_f32_16x16x32_bf16 v[64:67], v[156:159], v[214:217], v[64:67]
	v_mfma_f32_16x16x32_bf16 v[92:95], v[152:155], v[192:195], v[92:95]
	v_mfma_f32_16x16x32_bf16 v[88:91], v[168:171], v[192:195], v[88:91]
	v_mfma_f32_16x16x32_bf16 v[84:87], v[152:155], v[200:203], v[84:87]
	v_mfma_f32_16x16x32_bf16 v[80:83], v[168:171], v[200:203], v[80:83]
	v_mfma_f32_16x16x32_bf16 v[76:79], v[152:155], v[210:213], v[76:79]
	v_mfma_f32_16x16x32_bf16 v[72:75], v[168:171], v[210:213], v[72:75]
	v_mfma_f32_16x16x32_bf16 v[68:71], v[152:155], v[218:221], v[68:71]
	v_mfma_f32_16x16x32_bf16 v[64:67], v[168:171], v[218:221], v[64:67]
	v_mfma_f32_16x16x32_bf16 v[28:31], v[172:175], v[188:191], v[28:31]
	v_mfma_f32_16x16x32_bf16 v[24:27], v[180:183], v[188:191], v[24:27]
	v_mfma_f32_16x16x32_bf16 v[20:23], v[172:175], v[196:199], v[20:23]
	v_mfma_f32_16x16x32_bf16 v[16:19], v[180:183], v[196:199], v[16:19]
	v_mfma_f32_16x16x32_bf16 v[12:15], v[172:175], v[204:207], v[12:15]
	v_mfma_f32_16x16x32_bf16 v[8:11], v[180:183], v[204:207], v[8:11]
	v_mfma_f32_16x16x32_bf16 v[4:7], v[172:175], v[214:217], v[4:7]
	v_mfma_f32_16x16x32_bf16 v[0:3], v[180:183], v[214:217], v[0:3]
	v_mfma_f32_16x16x32_bf16 v[28:31], v[176:179], v[192:195], v[28:31]
	v_mfma_f32_16x16x32_bf16 v[24:27], v[184:187], v[192:195], v[24:27]
	v_mfma_f32_16x16x32_bf16 v[20:23], v[176:179], v[200:203], v[20:23]
	v_mfma_f32_16x16x32_bf16 v[16:19], v[184:187], v[200:203], v[16:19]
	v_mfma_f32_16x16x32_bf16 v[12:15], v[176:179], v[210:213], v[12:15]
	v_mfma_f32_16x16x32_bf16 v[8:11], v[184:187], v[210:213], v[8:11]
	v_mfma_f32_16x16x32_bf16 v[4:7], v[176:179], v[218:221], v[4:7]
	v_mfma_f32_16x16x32_bf16 v[0:3], v[184:187], v[218:221], v[0:3]
	s_barrier
	v_cvt_pk_bf16_f32 v148, v232, v234
	v_cvt_pk_bf16_f32 v149, v236, v238
	v_cvt_pk_bf16_f32 v152, v233, v235
	v_cvt_pk_bf16_f32 v153, v237, v239
	v_accvgpr_read_b32 v168, a0
	v_accvgpr_read_b32 v169, a2
	v_accvgpr_read_b32 v170, a4
	v_accvgpr_read_b32 v171, a6
	v_accvgpr_read_b32 v172, a1
	v_accvgpr_read_b32 v173, a3
	v_accvgpr_read_b32 v174, a5
	v_accvgpr_read_b32 v175, a7
	v_cvt_pk_bf16_f32 v150, v168, v169
	v_cvt_pk_bf16_f32 v151, v170, v171
	v_cvt_pk_bf16_f32 v154, v172, v173
	v_cvt_pk_bf16_f32 v155, v174, v175
	s_add_i32 s101, s101, 16
	s_cmp_lt_i32 s43, 14
	s_cbranch_scc0 .Lwc_keep
	s_lshl_b32 s32, s97, 11
	s_add_i32 s32, s32, 0x20000
	v_lshl_add_u32 v168, v208, 4, s32
	ds_write_b128 v168, v[148:151]
	ds_write_b128 v168, v[152:155] offset:1024
	s_branch .Lwc_packed

; #define PG8_STAGE(bufoff, gbase, voff) do { _Pragma("unroll") for (int _i = 0; _i < 2; ++_i) \
;         __builtin_amdgcn_global_load_lds((const unsigned*)((const char*)(gbase) + (voff)[_i]), (LAS unsigned*)(lds + (bufoff) + ldsw + _i * 8192), 16, 0, 0); } while (0)
; #define PG8_LDA(dst, b, h) do { _Pragma("unroll") for (int m = 0; m < 4; ++m) _Pragma("unroll") for (int k = 0; k < 2; ++k) dst[m][k] = *(const LAS bf16x8*)(lds + PG8_SA(b, h) + aoff + m * 2048 + k * 1024); } while (0)
; #define PG8_LDB(dst, b, h) do { _Pragma("unroll") for (int n = 0; n < 2; ++n) _Pragma("unroll") for (int k = 0; k < 2; ++k) dst[n][k] = *(const LAS bf16x8*)(lds + PG8_SB(b, h) + boff + n * 2048 + k * 1024); } while (0)
; #define PG8_MMA(ai, bj, At, Bt) do { __builtin_amdgcn_s_setprio(1); _Pragma("unroll") for (int m = 0; m < 4; ++m) _Pragma("unroll") for (int n = 0; n < 2; ++n) _Pragma("unroll") for (int k = 0; k < 2; ++k) \
;         acc[ai][bj][m][n] = __builtin_amdgcn_mfma_f32_16x16x32_bf16(Bt[n][k], At[m][k], acc[ai][bj][m][n], 0, 0, 0); __builtin_amdgcn_s_setprio(0); } while (0)
; #define PG8_WAIT_V(n) asm volatile("s_waitcnt vmcnt(" #n ")" ::: "memory")
; #define PG8_WAIT_L(n) asm volatile("s_waitcnt lgkmcnt(" #n ")" ::: "memory")
; #define PG8_BAR __builtin_amdgcn_s_barrier()
; #define PG8_SCHED __builtin_amdgcn_sched_barrier(0)
; template <class Epi, class Sched>
; __device__ __forceinline__ void gemm_phase(LAS unsigned char* lds, const Gemm g, const Sched& S, const Epi& E) {
;     ...
;             PG8_LDB(B0, 0, 0); PG8_LDB(B1, 0, 1); PG8_SCHED; PG8_LDA(At, 0, 0); PG8_STAGE(PG8_SA(1, 1), a1 + hstepA, voffA);
;             PG8_WAIT_V(8); PG8_WAIT_L(0); PG8_BAR; PG8_MMA(0, 0, At, B0); PG8_MMA(0, 1, At, B1); PG8_BAR; PG8_SCHED;
;             PG8_LDA(At, 0, 1); PG8_STAGE(PG8_SB(0, 0), b2, voffB); PG8_STAGE(PG8_SB(0, 1), b2 + hstepB, voffB); PG8_STAGE(PG8_SA(0, 0), a2, voffA);
;             PG8_WAIT_V(8); PG8_WAIT_L(0); PG8_BAR; PG8_MMA(1, 0, At, B0); PG8_MMA(1, 1, At, B1); PG8_BAR; PG8_SCHED;
.Lwc_N:
	ds_read_b128 v[148:151], v163
	ds_read_b128 v[152:155], v163 offset:1024
	ds_read_b128 v[156:159], v163 offset:2048
	ds_read_b128 v[168:171], v163 offset:3072
	ds_read_b128 v[172:175], v164
	ds_read_b128 v[176:179], v164 offset:1024
	ds_read_b128 v[180:183], v164 offset:2048
	ds_read_b128 v[184:187], v164 offset:3072
	s_add_u32 s2, s8, 0xfff80080
	s_addc_u32 s12, s9, -1
	s_cmp_eq_u32 s43, 28
	s_cselect_b32 s41, s7, s12
	s_cselect_b32 s40, s11, s2
	s_cselect_b32 s13, s31, s42
	s_cselect_b32 s12, s33, s35
	v_lshl_add_u64 v[222:223], s[8:9], 0, v[140:141]
	s_add_i32 m0, s53, 0xc000
	ds_read_b128 v[188:191], v165
	ds_read_b128 v[192:195], v165 offset:1024
	ds_read_b128 v[196:199], v165 offset:2048
	ds_read_b128 v[200:203], v165 offset:3072
	ds_read_b128 v[204:207], v165 offset:4096
	ds_read_b128 v[210:213], v165 offset:5120
	ds_read_b128 v[214:217], v165 offset:6144
	ds_read_b128 v[218:221], v165 offset:7168
	global_load_lds_dwordx4 v[222:223], off
	v_lshl_add_u64 v[222:223], s[8:9], 0, v[142:143]
	s_add_i32 m0, s53, 0xe000
	s_nop 0
	global_load_lds_dwordx4 v[222:223], off
	s_waitcnt vmcnt(8)
	s_waitcnt lgkmcnt(0)
	s_barrier
	s_waitcnt lgkmcnt(0)
	v_mfma_f32_16x16x32_bf16 v[124:127], v[148:151], v[188:191], v[124:127]
	v_mfma_f32_16x16x32_bf16 v[120:123], v[156:159], v[188:191], v[120:123]
	v_mfma_f32_16x16x32_bf16 v[116:119], v[148:151], v[196:199], v[116:119]
	v_mfma_f32_16x16x32_bf16 v[112:115], v[156:159], v[196:199], v[112:115]
	v_mfma_f32_16x16x32_bf16 v[108:111], v[148:151], v[204:207], v[108:111]
	v_mfma_f32_16x16x32_bf16 v[104:107], v[156:159], v[204:207], v[104:107]
	v_mfma_f32_16x16x32_bf16 v[100:103], v[148:151], v[214:217], v[100:103]
	v_mfma_f32_16x16x32_bf16 v[96:99], v[156:159], v[214:217], v[96:99]
	v_mfma_f32_16x16x32_bf16 v[124:127], v[152:155], v[192:195], v[124:127]
	v_mfma_f32_16x16x32_bf16 v[120:123], v[168:171], v[192:195], v[120:123]
	v_mfma_f32_16x16x32_bf16 v[116:119], v[152:155], v[200:203], v[116:119]
	v_mfma_f32_16x16x32_bf16 v[112:115], v[168:171], v[200:203], v[112:115]
	v_mfma_f32_16x16x32_bf16 v[108:111], v[152:155], v[210:213], v[108:111]
	v_mfma_f32_16x16x32_bf16 v[104:107], v[168:171], v[210:213], v[104:107]
	v_mfma_f32_16x16x32_bf16 v[100:103], v[152:155], v[218:221], v[100:103]
	v_mfma_f32_16x16x32_bf16 v[96:99], v[168:171], v[218:221], v[96:99]
	v_mfma_f32_16x16x32_bf16 v[60:63], v[172:175], v[188:191], v[60:63]
	v_mfma_f32_16x16x32_bf16 v[56:59], v[180:183], v[188:191], v[56:59]
	v_mfma_f32_16x16x32_bf16 v[52:55], v[172:175], v[196:199], v[52:55]
	v_mfma_f32_16x16x32_bf16 v[48:51], v[180:183], v[196:199], v[48:51]
	v_mfma_f32_16x16x32_bf16 v[44:47], v[172:175], v[204:207], v[44:47]
	v_mfma_f32_16x16x32_bf16 v[40:43], v[180:183], v[204:207], v[40:43]
	v_mfma_f32_16x16x32_bf16 v[36:39], v[172:175], v[214:217], v[36:39]
	v_mfma_f32_16x16x32_bf16 v[32:35], v[180:183], v[214:217], v[32:35]
	v_mfma_f32_16x16x32_bf16 v[60:63], v[176:179], v[192:195], v[60:63]
	v_mfma_f32_16x16x32_bf16 v[56:59], v[184:187], v[192:195], v[56:59]
	v_mfma_f32_16x16x32_bf16 v[52:55], v[176:179], v[200:203], v[52:55]
	v_mfma_f32_16x16x32_bf16 v[48:51], v[184:187], v[200:203], v[48:51]
	v_mfma_f32_16x16x32_bf16 v[44:47], v[176:179], v[210:213], v[44:47]
	v_mfma_f32_16x16x32_bf16 v[40:43], v[184:187], v[210:213], v[40:43]
	v_mfma_f32_16x16x32_bf16 v[36:39], v[176:179], v[218:221], v[36:39]
	v_mfma_f32_16x16x32_bf16 v[32:35], v[184:187], v[218:221], v[32:35]
	s_barrier
	s_add_i32 s2, s64, s52
	v_lshl_add_u64 v[222:223], s[12:13], 0, v[130:131]
	s_mov_b32 m0, s2
	ds_read_b128 v[188:191], v165 offset:16384
	ds_read_b128 v[192:195], v165 offset:17408
	ds_read_b128 v[196:199], v165 offset:18432
	ds_read_b128 v[200:203], v165 offset:19456
	ds_read_b128 v[204:207], v165 offset:20480
	ds_read_b128 v[210:213], v165 offset:21504
	ds_read_b128 v[214:217], v165 offset:22528
	ds_read_b128 v[218:221], v165 offset:23552
	global_load_lds_dwordx4 v[222:223], off
	s_add_i32 m0, s2, 0x2000
	s_add_u32 s44, s12, 0x80000
	v_lshl_add_u64 v[224:225], s[12:13], 0, v[134:135]
	s_addc_u32 s45, s13, 0
	s_add_i32 s2, s65, s52
	global_load_lds_dwordx4 v[224:225], off
	v_lshl_add_u64 v[226:227], s[44:45], 0, v[130:131]
	s_mov_b32 m0, s2
	v_lshl_add_u64 v[228:229], s[40:41], 0, v[132:133]
	global_load_lds_dwordx4 v[226:227], off
	v_lshl_add_u64 v[226:227], s[44:45], 0, v[134:135]
	s_add_i32 m0, s2, 0x2000
	s_nop 0
	global_load_lds_dwordx4 v[226:227], off
	v_lshl_add_u64 v[226:227], s[40:41], 0, v[128:129]
	s_mov_b32 m0, s53
	s_nop 0
	global_load_lds_dwordx4 v[226:227], off
	s_mov_b32 m0, s54
	s_nop 0
	global_load_lds_dwordx4 v[228:229], off
	s_waitcnt vmcnt(8)
	s_waitcnt lgkmcnt(0)
	s_barrier
; #define PG8_STAGE(bufoff, gbase, voff) do { _Pragma("unroll") for (int _i = 0; _i < 2; ++_i) \
;         __builtin_amdgcn_global_load_lds((const unsigned*)((const char*)(gbase) + (voff)[_i]), (LAS unsigned*)(lds + (bufoff) + ldsw + _i * 8192), 16, 0, 0); } while (0)
; #define PG8_LDA(dst, b, h) do { _Pragma("unroll") for (int m = 0; m < 4; ++m) _Pragma("unroll") for (int k = 0; k < 2; ++k) dst[m][k] = *(const LAS bf16x8*)(lds + PG8_SA(b, h) + aoff + m * 2048 + k * 1024); } while (0)
; #define PG8_LDB(dst, b, h) do { _Pragma("unroll") for (int n = 0; n < 2; ++n) _Pragma("unroll") for (int k = 0; k < 2; ++k) dst[n][k] = *(const LAS bf16x8*)(lds + PG8_SB(b, h) + boff + n * 2048 + k * 1024); } while (0)
; #define PG8_MMA(ai, bj, At, Bt) do { __builtin_amdgcn_s_setprio(1); _Pragma("unroll") for (int m = 0; m < 4; ++m) _Pragma("unroll") for (int n = 0; n < 2; ++n) _Pragma("unroll") for (int k = 0; k < 2; ++k) \
;         acc[ai][bj][m][n] = __builtin_amdgcn_mfma_f32_16x16x32_bf16(Bt[n][k], At[m][k], acc[ai][bj][m][n], 0, 0, 0); __builtin_amdgcn_s_setprio(0); } while (0)
; #define PG8_WAIT_V(n) asm volatile("s_waitcnt vmcnt(" #n ")" ::: "memory")
; #define PG8_WAIT_L(n) asm volatile("s_waitcnt lgkmcnt(" #n ")" ::: "memory")
; #define PG8_BAR __builtin_amdgcn_s_barrier()
; #define PG8_SCHED __builtin_amdgcn_sched_barrier(0)
; template <class Epi, class Sched>
; __device__ __forceinline__ void gemm_phase(LAS unsigned char* lds, const Gemm g, const Sched& S, const Epi& E) {
;     ...
;             PG8_WAIT_V(8); PG8_WAIT_L(0); PG8_BAR; PG8_MMA(1, 0, At, B0); PG8_MMA(1, 1, At, B1); PG8_BAR; PG8_SCHED;
;             PG8_LDB(B0, 1, 0); PG8_LDB(B1, 1, 1); PG8_SCHED; PG8_LDA(At, 1, 0); PG8_STAGE(PG8_SA(0, 1), a2 + hstepA, voffA);
;             PG8_WAIT_V(8); PG8_WAIT_L(0); PG8_BAR; PG8_MMA(0, 0, At, B0); PG8_MMA(0, 1, At, B1); PG8_BAR; PG8_SCHED;
;             PG8_LDA(At, 1, 1); PG8_STAGE(PG8_SB(1, 0), b3, voffB); PG8_STAGE(PG8_SB(1, 1), b3 + hstepB, voffB); PG8_STAGE(PG8_SA(1, 0), a3, voffA);
	s_waitcnt lgkmcnt(0)
	v_mfma_f32_16x16x32_bf16 v[92:95], v[148:151], v[188:191], v[92:95]
	v_mfma_f32_16x16x32_bf16 v[88:91], v[156:159], v[188:191], v[88:91]
	v_mfma_f32_16x16x32_bf16 v[84:87], v[148:151], v[196:199], v[84:87]
	v_mfma_f32_16x16x32_bf16 v[80:83], v[156:159], v[196:199], v[80:83]
	v_mfma_f32_16x16x32_bf16 v[76:79], v[148:151], v[204:207], v[76:79]
	v_mfma_f32_16x16x32_bf16 v[72:75], v[156:159], v[204:207], v[72:75]
	v_mfma_f32_16x16x32_bf16 v[68:71], v[148:151], v[214:217], v[68:71]
	v_mfma_f32_16x16x32_bf16 v[64:67], v[156:159], v[214:217], v[64:67]
	v_mfma_f32_16x16x32_bf16 v[92:95], v[152:155], v[192:195], v[92:95]
	v_mfma_f32_16x16x32_bf16 v[88:91], v[168:171], v[192:195], v[88:91]
	v_mfma_f32_16x16x32_bf16 v[84:87], v[152:155], v[200:203], v[84:87]
	v_mfma_f32_16x16x32_bf16 v[80:83], v[168:171], v[200:203], v[80:83]
	v_mfma_f32_16x16x32_bf16 v[76:79], v[152:155], v[210:213], v[76:79]
	v_mfma_f32_16x16x32_bf16 v[72:75], v[168:171], v[210:213], v[72:75]
	v_mfma_f32_16x16x32_bf16 v[68:71], v[152:155], v[218:221], v[68:71]
	v_mfma_f32_16x16x32_bf16 v[64:67], v[168:171], v[218:221], v[64:67]
	v_mfma_f32_16x16x32_bf16 v[28:31], v[172:175], v[188:191], v[28:31]
	v_mfma_f32_16x16x32_bf16 v[24:27], v[180:183], v[188:191], v[24:27]
	v_mfma_f32_16x16x32_bf16 v[20:23], v[172:175], v[196:199], v[20:23]
	v_mfma_f32_16x16x32_bf16 v[16:19], v[180:183], v[196:199], v[16:19]
	v_mfma_f32_16x16x32_bf16 v[12:15], v[172:175], v[204:207], v[12:15]
	v_mfma_f32_16x16x32_bf16 v[8:11], v[180:183], v[204:207], v[8:11]
	v_mfma_f32_16x16x32_bf16 v[4:7], v[172:175], v[214:217], v[4:7]
	v_mfma_f32_16x16x32_bf16 v[0:3], v[180:183], v[214:217], v[0:3]
	v_mfma_f32_16x16x32_bf16 v[28:31], v[176:179], v[192:195], v[28:31]
	v_mfma_f32_16x16x32_bf16 v[24:27], v[184:187], v[192:195], v[24:27]
	v_mfma_f32_16x16x32_bf16 v[20:23], v[176:179], v[200:203], v[20:23]
	v_mfma_f32_16x16x32_bf16 v[16:19], v[184:187], v[200:203], v[16:19]
	v_mfma_f32_16x16x32_bf16 v[12:15], v[176:179], v[210:213], v[12:15]
	v_mfma_f32_16x16x32_bf16 v[8:11], v[184:187], v[210:213], v[8:11]
	v_mfma_f32_16x16x32_bf16 v[4:7], v[176:179], v[218:221], v[4:7]
	v_mfma_f32_16x16x32_bf16 v[0:3], v[184:187], v[218:221], v[0:3]
	s_barrier
	s_add_i32 s2, 0, 0x18000
	v_add_u32_e32 v136, s2, v161
	s_add_i32 s44, 0, 0x1c000
	ds_read_b128 v[148:151], v136
	ds_read_b128 v[152:155], v136 offset:1024
	ds_read_b128 v[156:159], v136 offset:2048
	ds_read_b128 v[168:171], v136 offset:3072
	v_add_u32_e32 v136, s44, v161
	ds_read_b128 v[172:175], v136
	ds_read_b128 v[176:179], v136 offset:1024
	ds_read_b128 v[180:183], v136 offset:2048
	ds_read_b128 v[184:187], v136 offset:3072
	s_add_u32 s40, s40, 0x80000
	s_addc_u32 s41, s41, 0
	s_mov_b32 m0, s55
	v_lshl_add_u64 v[230:231], s[40:41], 0, v[128:129]
	ds_read_b128 v[188:191], v165 offset:32768
	ds_read_b128 v[192:195], v165 offset:33792
	ds_read_b128 v[196:199], v165 offset:34816
	ds_read_b128 v[200:203], v165 offset:35840
	ds_read_b128 v[204:207], v165 offset:36864
	ds_read_b128 v[210:213], v165 offset:37888
	ds_read_b128 v[214:217], v165 offset:38912
	ds_read_b128 v[218:221], v165 offset:39936
	global_load_lds_dwordx4 v[230:231], off
	v_lshl_add_u64 v[230:231], s[40:41], 0, v[132:133]
	s_mov_b32 m0, s56
	s_nop 0
	global_load_lds_dwordx4 v[230:231], off
	s_waitcnt vmcnt(8)
	s_waitcnt lgkmcnt(0)
	s_barrier
	s_waitcnt lgkmcnt(0)
	v_mfma_f32_16x16x32_bf16 v[124:127], v[148:151], v[188:191], v[124:127]
	v_mfma_f32_16x16x32_bf16 v[120:123], v[156:159], v[188:191], v[120:123]
	v_mfma_f32_16x16x32_bf16 v[116:119], v[148:151], v[196:199], v[116:119]
	v_mfma_f32_16x16x32_bf16 v[112:115], v[156:159], v[196:199], v[112:115]
	v_mfma_f32_16x16x32_bf16 v[108:111], v[148:151], v[204:207], v[108:111]
	v_mfma_f32_16x16x32_bf16 v[104:107], v[156:159], v[204:207], v[104:107]
	v_mfma_f32_16x16x32_bf16 v[100:103], v[148:151], v[214:217], v[100:103]
	v_mfma_f32_16x16x32_bf16 v[96:99], v[156:159], v[214:217], v[96:99]
	v_mfma_f32_16x16x32_bf16 v[124:127], v[152:155], v[192:195], v[124:127]
	v_mfma_f32_16x16x32_bf16 v[120:123], v[168:171], v[192:195], v[120:123]
	v_mfma_f32_16x16x32_bf16 v[116:119], v[152:155], v[200:203], v[116:119]
	v_mfma_f32_16x16x32_bf16 v[112:115], v[168:171], v[200:203], v[112:115]
	v_mfma_f32_16x16x32_bf16 v[108:111], v[152:155], v[210:213], v[108:111]
	v_mfma_f32_16x16x32_bf16 v[104:107], v[168:171], v[210:213], v[104:107]
	v_mfma_f32_16x16x32_bf16 v[100:103], v[152:155], v[218:221], v[100:103]
	v_mfma_f32_16x16x32_bf16 v[96:99], v[168:171], v[218:221], v[96:99]
	v_mfma_f32_16x16x32_bf16 v[60:63], v[172:175], v[188:191], v[60:63]
	v_mfma_f32_16x16x32_bf16 v[56:59], v[180:183], v[188:191], v[56:59]
	v_mfma_f32_16x16x32_bf16 v[52:55], v[172:175], v[196:199], v[52:55]
	v_mfma_f32_16x16x32_bf16 v[48:51], v[180:183], v[196:199], v[48:51]
	v_mfma_f32_16x16x32_bf16 v[44:47], v[172:175], v[204:207], v[44:47]
	v_mfma_f32_16x16x32_bf16 v[40:43], v[180:183], v[204:207], v[40:43]
	v_mfma_f32_16x16x32_bf16 v[36:39], v[172:175], v[214:217], v[36:39]
	v_mfma_f32_16x16x32_bf16 v[32:35], v[180:183], v[214:217], v[32:35]
	v_mfma_f32_16x16x32_bf16 v[60:63], v[176:179], v[192:195], v[60:63]
	v_mfma_f32_16x16x32_bf16 v[56:59], v[184:187], v[192:195], v[56:59]
	v_mfma_f32_16x16x32_bf16 v[52:55], v[176:179], v[200:203], v[52:55]
	v_mfma_f32_16x16x32_bf16 v[48:51], v[184:187], v[200:203], v[48:51]
	v_mfma_f32_16x16x32_bf16 v[44:47], v[176:179], v[210:213], v[44:47]
	v_mfma_f32_16x16x32_bf16 v[40:43], v[184:187], v[210:213], v[40:43]
	v_mfma_f32_16x16x32_bf16 v[36:39], v[176:179], v[218:221], v[36:39]
	v_mfma_f32_16x16x32_bf16 v[32:35], v[184:187], v[218:221], v[32:35]
	s_barrier
; #define PG8_STAGE(bufoff, gbase, voff) do { _Pragma("unroll") for (int _i = 0; _i < 2; ++_i) \
;         __builtin_amdgcn_global_load_lds((const unsigned*)((const char*)(gbase) + (voff)[_i]), (LAS unsigned*)(lds + (bufoff) + ldsw + _i * 8192), 16, 0, 0); } while (0)
; #define PG8_LDA(dst, b, h) do { _Pragma("unroll") for (int m = 0; m < 4; ++m) _Pragma("unroll") for (int k = 0; k < 2; ++k) dst[m][k] = *(const LAS bf16x8*)(lds + PG8_SA(b, h) + aoff + m * 2048 + k * 1024); } while (0)
; #define PG8_MMA(ai, bj, At, Bt) do { __builtin_amdgcn_s_setprio(1); _Pragma("unroll") for (int m = 0; m < 4; ++m) _Pragma("unroll") for (int n = 0; n < 2; ++n) _Pragma("unroll") for (int k = 0; k < 2; ++k) \
;         acc[ai][bj][m][n] = __builtin_amdgcn_mfma_f32_16x16x32_bf16(Bt[n][k], At[m][k], acc[ai][bj][m][n], 0, 0, 0); __builtin_amdgcn_s_setprio(0); } while (0)
; #define PG8_WAIT_V(n) asm volatile("s_waitcnt vmcnt(" #n ")" ::: "memory")
; #define PG8_WAIT_L(n) asm volatile("s_waitcnt lgkmcnt(" #n ")" ::: "memory")
; #define PG8_BAR __builtin_amdgcn_s_barrier()
; #define PG8_SCHED __builtin_amdgcn_sched_barrier(0)
; template <class Epi, class Sched>
; __device__ __forceinline__ void gemm_phase(LAS unsigned char* lds, const Gemm g, const Sched& S, const Epi& E) {
;     ...
;             PG8_LDA(At, 1, 1); PG8_STAGE(PG8_SB(1, 0), b3, voffB); PG8_STAGE(PG8_SB(1, 1), b3 + hstepB, voffB); PG8_STAGE(PG8_SA(1, 0), a3, voffA);
;             PG8_WAIT_V(8); PG8_WAIT_L(0); PG8_BAR; PG8_MMA(1, 0, At, B0); PG8_MMA(1, 1, At, B1); PG8_BAR; PG8_SCHED;
;         }
	s_add_i32 s2, s2, s52
	v_lshl_add_u64 v[222:223], v[222:223], 0, s[18:19]
	s_mov_b32 m0, s2
	ds_read_b128 v[188:191], v165 offset:49152
	ds_read_b128 v[192:195], v165 offset:50176
	ds_read_b128 v[196:199], v165 offset:51200
	ds_read_b128 v[200:203], v165 offset:52224
	ds_read_b128 v[204:207], v165 offset:53248
	ds_read_b128 v[210:213], v165 offset:54272
	ds_read_b128 v[214:217], v165 offset:55296
	ds_read_b128 v[218:221], v165 offset:56320
	global_load_lds_dwordx4 v[222:223], off
	s_add_i32 m0, s2, 0x2000
	s_add_u32 s12, s12, 0x80080
	v_lshl_add_u64 v[222:223], v[224:225], 0, s[18:19]
	s_addc_u32 s13, s13, 0
	s_add_i32 s2, s44, s52
	global_load_lds_dwordx4 v[222:223], off
	v_lshl_add_u64 v[222:223], s[12:13], 0, v[130:131]
	s_mov_b32 m0, s2
	s_nop 0
	global_load_lds_dwordx4 v[222:223], off
	v_lshl_add_u64 v[222:223], s[12:13], 0, v[134:135]
	s_add_i32 m0, s2, 0x2000
	s_nop 0
	global_load_lds_dwordx4 v[222:223], off
	v_lshl_add_u64 v[222:223], v[226:227], 0, s[18:19]
	s_mov_b32 m0, s58
	s_nop 0
	global_load_lds_dwordx4 v[222:223], off
	v_lshl_add_u64 v[222:223], v[228:229], 0, s[18:19]
	s_mov_b32 m0, s59
	s_nop 0
	global_load_lds_dwordx4 v[222:223], off
	s_waitcnt vmcnt(8)
	s_waitcnt lgkmcnt(0)
	s_barrier
	s_waitcnt lgkmcnt(0)
	v_mfma_f32_16x16x32_bf16 v[92:95], v[148:151], v[188:191], v[92:95]
	v_mfma_f32_16x16x32_bf16 v[88:91], v[156:159], v[188:191], v[88:91]
	v_mfma_f32_16x16x32_bf16 v[84:87], v[148:151], v[196:199], v[84:87]
	v_mfma_f32_16x16x32_bf16 v[80:83], v[156:159], v[196:199], v[80:83]
	v_mfma_f32_16x16x32_bf16 v[76:79], v[148:151], v[204:207], v[76:79]
	v_mfma_f32_16x16x32_bf16 v[72:75], v[156:159], v[204:207], v[72:75]
	v_mfma_f32_16x16x32_bf16 v[68:71], v[148:151], v[214:217], v[68:71]
	v_mfma_f32_16x16x32_bf16 v[64:67], v[156:159], v[214:217], v[64:67]
	v_mfma_f32_16x16x32_bf16 v[92:95], v[152:155], v[192:195], v[92:95]
	v_mfma_f32_16x16x32_bf16 v[88:91], v[168:171], v[192:195], v[88:91]
	v_mfma_f32_16x16x32_bf16 v[84:87], v[152:155], v[200:203], v[84:87]
	v_mfma_f32_16x16x32_bf16 v[80:83], v[168:171], v[200:203], v[80:83]
	v_mfma_f32_16x16x32_bf16 v[76:79], v[152:155], v[210:213], v[76:79]
	v_mfma_f32_16x16x32_bf16 v[72:75], v[168:171], v[210:213], v[72:75]
	v_mfma_f32_16x16x32_bf16 v[68:71], v[152:155], v[218:221], v[68:71]
	v_mfma_f32_16x16x32_bf16 v[64:67], v[168:171], v[218:221], v[64:67]
	v_mfma_f32_16x16x32_bf16 v[28:31], v[172:175], v[188:191], v[28:31]
	v_mfma_f32_16x16x32_bf16 v[24:27], v[180:183], v[188:191], v[24:27]
	v_mfma_f32_16x16x32_bf16 v[20:23], v[172:175], v[196:199], v[20:23]
	v_mfma_f32_16x16x32_bf16 v[16:19], v[180:183], v[196:199], v[16:19]
	v_mfma_f32_16x16x32_bf16 v[12:15], v[172:175], v[204:207], v[12:15]
	v_mfma_f32_16x16x32_bf16 v[8:11], v[180:183], v[204:207], v[8:11]
	v_mfma_f32_16x16x32_bf16 v[4:7], v[172:175], v[214:217], v[4:7]
	v_mfma_f32_16x16x32_bf16 v[0:3], v[180:183], v[214:217], v[0:3]
	v_mfma_f32_16x16x32_bf16 v[28:31], v[176:179], v[192:195], v[28:31]
	v_mfma_f32_16x16x32_bf16 v[24:27], v[184:187], v[192:195], v[24:27]
	v_mfma_f32_16x16x32_bf16 v[20:23], v[176:179], v[200:203], v[20:23]
	v_mfma_f32_16x16x32_bf16 v[16:19], v[184:187], v[200:203], v[16:19]
	v_mfma_f32_16x16x32_bf16 v[12:15], v[176:179], v[210:213], v[12:15]
	v_mfma_f32_16x16x32_bf16 v[8:11], v[184:187], v[210:213], v[8:11]
	v_mfma_f32_16x16x32_bf16 v[4:7], v[176:179], v[218:221], v[4:7]
	v_mfma_f32_16x16x32_bf16 v[0:3], v[184:187], v[218:221], v[0:3]
	s_barrier
	s_add_i32 s43, s43, 2
	s_add_u32 s8, s8, 0x100
	s_addc_u32 s9, s9, 0
	s_add_u32 s35, s35, 0x100
	s_addc_u32 s42, s42, 0
	s_cmp_gt_u32 s43, 29
	s_cbranch_scc1 .Lwc_exit
	s_cmp_eq_u32 s43, s101
	s_cbranch_scc1 .LBB0_178
	s_branch .Lwc_N

; #define PG8_STAGE(bufoff, gbase, voff) do { _Pragma("unroll") for (int _i = 0; _i < 2; ++_i) \
;         __builtin_amdgcn_global_load_lds((const unsigned*)((const char*)(gbase) + (voff)[_i]), (LAS unsigned*)(lds + (bufoff) + ldsw + _i * 8192), 16, 0, 0); } while (0)
; #define PG8_LDA(dst, b, h) do { _Pragma("unroll") for (int m = 0; m < 4; ++m) _Pragma("unroll") for (int k = 0; k < 2; ++k) dst[m][k] = *(const LAS bf16x8*)(lds + PG8_SA(b, h) + aoff + m * 2048 + k * 1024); } while (0)
; #define PG8_LDB(dst, b, h) do { _Pragma("unroll") for (int n = 0; n < 2; ++n) _Pragma("unroll") for (int k = 0; k < 2; ++k) dst[n][k] = *(const LAS bf16x8*)(lds + PG8_SB(b, h) + boff + n * 2048 + k * 1024); } while (0)
; #define PG8_MMA(ai, bj, At, Bt) do { __builtin_amdgcn_s_setprio(1); _Pragma("unroll") for (int m = 0; m < 4; ++m) _Pragma("unroll") for (int n = 0; n < 2; ++n) _Pragma("unroll") for (int k = 0; k < 2; ++k) \
;         acc[ai][bj][m][n] = __builtin_amdgcn_mfma_f32_16x16x32_bf16(Bt[n][k], At[m][k], acc[ai][bj][m][n], 0, 0, 0); __builtin_amdgcn_s_setprio(0); } while (0)
; #define PG8_WAIT_V(n) asm volatile("s_waitcnt vmcnt(" #n ")" ::: "memory")
; #define PG8_WAIT_L(n) asm volatile("s_waitcnt lgkmcnt(" #n ")" ::: "memory")
; #define PG8_BAR __builtin_amdgcn_s_barrier()
; #define PG8_SCHED __builtin_amdgcn_sched_barrier(0)
; template <class Epi, class Sched>
; __device__ __forceinline__ void gemm_phase(LAS unsigned char* lds, const Gemm g, const Sched& S, const Epi& E) {
;     ...
;             PG8_LDB(B0, 0, 0); PG8_LDB(B1, 0, 1); PG8_SCHED; PG8_LDA(At, 0, 0); PG8_STAGE(PG8_SA(1, 1), a1 + hstepA, voffA);
;             PG8_WAIT_V(8); PG8_WAIT_L(0); PG8_BAR; PG8_MMA(0, 0, At, B0); PG8_MMA(0, 1, At, B1); PG8_BAR; PG8_SCHED;
;             PG8_LDA(At, 0, 1); PG8_STAGE(PG8_SB(0, 0), b2, voffB); PG8_STAGE(PG8_SB(0, 1), b2 + hstepB, voffB); PG8_STAGE(PG8_SA(0, 0), a2, voffA);
;             PG8_WAIT_V(8); PG8_WAIT_L(0); PG8_BAR; PG8_MMA(1, 0, At, B0); PG8_MMA(1, 1, At, B1); PG8_BAR; PG8_SCHED;
.LBB0_807:
	ds_read_b128 v[128:131], v163
	ds_read_b128 v[132:135], v163 offset:1024
	ds_read_b128 v[136:139], v163 offset:2048
	ds_read_b128 v[140:143], v163 offset:3072
	ds_read_b128 v[166:169], v164
	ds_read_b128 v[170:173], v164 offset:1024
	ds_read_b128 v[174:177], v164 offset:2048
	ds_read_b128 v[178:181], v164 offset:3072
	s_add_u32 s2, s36, 0xfff80080
	s_addc_u32 s38, s37, -1
	s_cmp_eq_u32 s65, 28
	s_cselect_b32 s41, s27, s38
	s_cselect_b32 s40, s33, s2
	s_cselect_b32 s39, s25, s64
	s_cselect_b32 s38, s62, s63
	v_lshl_add_u64 v[218:219], s[36:37], 0, v[152:153]
	s_add_i32 m0, s35, 0xc000
	ds_read_b128 v[182:185], v165
	ds_read_b128 v[186:189], v165 offset:1024
	ds_read_b128 v[192:195], v165 offset:2048
	ds_read_b128 v[196:199], v165 offset:3072
	ds_read_b128 v[200:203], v165 offset:4096
	ds_read_b128 v[204:207], v165 offset:5120
	ds_read_b128 v[210:213], v165 offset:6144
	ds_read_b128 v[214:217], v165 offset:7168
	global_load_lds_dwordx4 v[218:219], off
	v_lshl_add_u64 v[218:219], s[36:37], 0, v[154:155]
	s_add_i32 m0, s35, 0xe000
	s_nop 0
	global_load_lds_dwordx4 v[218:219], off
	s_waitcnt vmcnt(8)
	s_waitcnt lgkmcnt(0)
	s_barrier
	s_waitcnt lgkmcnt(0)
	v_mfma_f32_16x16x32_bf16 v[124:127], v[128:131], v[182:185], v[124:127]
	v_mfma_f32_16x16x32_bf16 v[120:123], v[136:139], v[182:185], v[120:123]
	v_mfma_f32_16x16x32_bf16 v[116:119], v[128:131], v[192:195], v[116:119]
	v_mfma_f32_16x16x32_bf16 v[112:115], v[136:139], v[192:195], v[112:115]
	v_mfma_f32_16x16x32_bf16 v[108:111], v[128:131], v[200:203], v[108:111]
	v_mfma_f32_16x16x32_bf16 v[100:103], v[136:139], v[200:203], v[100:103]
	v_mfma_f32_16x16x32_bf16 v[92:95], v[128:131], v[210:213], v[92:95]
	v_mfma_f32_16x16x32_bf16 v[72:75], v[136:139], v[210:213], v[72:75]
	v_mfma_f32_16x16x32_bf16 v[124:127], v[132:135], v[186:189], v[124:127]
	v_mfma_f32_16x16x32_bf16 v[120:123], v[140:143], v[186:189], v[120:123]
	v_mfma_f32_16x16x32_bf16 v[116:119], v[132:135], v[196:199], v[116:119]
	v_mfma_f32_16x16x32_bf16 v[112:115], v[140:143], v[196:199], v[112:115]
	v_mfma_f32_16x16x32_bf16 v[108:111], v[132:135], v[204:207], v[108:111]
	v_mfma_f32_16x16x32_bf16 v[100:103], v[140:143], v[204:207], v[100:103]
	v_mfma_f32_16x16x32_bf16 v[92:95], v[132:135], v[214:217], v[92:95]
	v_mfma_f32_16x16x32_bf16 v[72:75], v[140:143], v[214:217], v[72:75]
	v_mfma_f32_16x16x32_bf16 v[104:107], v[166:169], v[182:185], v[104:107]
	v_mfma_f32_16x16x32_bf16 v[96:99], v[174:177], v[182:185], v[96:99]
	v_mfma_f32_16x16x32_bf16 v[88:91], v[166:169], v[192:195], v[88:91]
	v_mfma_f32_16x16x32_bf16 v[84:87], v[174:177], v[192:195], v[84:87]
	v_mfma_f32_16x16x32_bf16 v[80:83], v[166:169], v[200:203], v[80:83]
	v_mfma_f32_16x16x32_bf16 v[76:79], v[174:177], v[200:203], v[76:79]
	v_mfma_f32_16x16x32_bf16 v[68:71], v[166:169], v[210:213], v[68:71]
	v_mfma_f32_16x16x32_bf16 v[64:67], v[174:177], v[210:213], v[64:67]
	v_mfma_f32_16x16x32_bf16 v[104:107], v[170:173], v[186:189], v[104:107]
	v_mfma_f32_16x16x32_bf16 v[96:99], v[178:181], v[186:189], v[96:99]
	v_mfma_f32_16x16x32_bf16 v[88:91], v[170:173], v[196:199], v[88:91]
	v_mfma_f32_16x16x32_bf16 v[84:87], v[178:181], v[196:199], v[84:87]
	v_mfma_f32_16x16x32_bf16 v[80:83], v[170:173], v[204:207], v[80:83]
	v_mfma_f32_16x16x32_bf16 v[76:79], v[178:181], v[204:207], v[76:79]
	v_mfma_f32_16x16x32_bf16 v[68:71], v[170:173], v[214:217], v[68:71]
	v_mfma_f32_16x16x32_bf16 v[64:67], v[178:181], v[214:217], v[64:67]
	s_barrier
	s_add_i32 s2, s55, s46
	v_lshl_add_u64 v[218:219], s[38:39], 0, v[146:147]
	s_mov_b32 m0, s2
	ds_read_b128 v[182:185], v165 offset:16384
	ds_read_b128 v[186:189], v165 offset:17408
	ds_read_b128 v[192:195], v165 offset:18432
	ds_read_b128 v[196:199], v165 offset:19456
	ds_read_b128 v[200:203], v165 offset:20480
	ds_read_b128 v[204:207], v165 offset:21504
	ds_read_b128 v[210:213], v165 offset:22528
	ds_read_b128 v[214:217], v165 offset:23552
	global_load_lds_dwordx4 v[218:219], off
	s_add_i32 m0, s2, 0x2000
	s_add_u32 s66, s38, 0x80000
	v_lshl_add_u64 v[220:221], s[38:39], 0, v[150:151]
	s_addc_u32 s67, s39, 0
	s_add_i32 s2, s56, s46
	global_load_lds_dwordx4 v[220:221], off
	v_lshl_add_u64 v[222:223], s[66:67], 0, v[146:147]
	s_mov_b32 m0, s2
	v_lshl_add_u64 v[224:225], s[40:41], 0, v[148:149]
	global_load_lds_dwordx4 v[222:223], off
	v_lshl_add_u64 v[222:223], s[66:67], 0, v[150:151]
	s_add_i32 m0, s2, 0x2000
	s_nop 0
	global_load_lds_dwordx4 v[222:223], off
	v_lshl_add_u64 v[222:223], s[40:41], 0, v[144:145]
	s_mov_b32 m0, s35
	s_nop 0
	global_load_lds_dwordx4 v[222:223], off
	s_mov_b32 m0, s47
	s_nop 0
	global_load_lds_dwordx4 v[224:225], off
	s_waitcnt vmcnt(8)
	s_waitcnt lgkmcnt(0)
	s_barrier
; #define PG8_STAGE(bufoff, gbase, voff) do { _Pragma("unroll") for (int _i = 0; _i < 2; ++_i) \
;         __builtin_amdgcn_global_load_lds((const unsigned*)((const char*)(gbase) + (voff)[_i]), (LAS unsigned*)(lds + (bufoff) + ldsw + _i * 8192), 16, 0, 0); } while (0)
; #define PG8_LDA(dst, b, h) do { _Pragma("unroll") for (int m = 0; m < 4; ++m) _Pragma("unroll") for (int k = 0; k < 2; ++k) dst[m][k] = *(const LAS bf16x8*)(lds + PG8_SA(b, h) + aoff + m * 2048 + k * 1024); } while (0)
; #define PG8_LDB(dst, b, h) do { _Pragma("unroll") for (int n = 0; n < 2; ++n) _Pragma("unroll") for (int k = 0; k < 2; ++k) dst[n][k] = *(const LAS bf16x8*)(lds + PG8_SB(b, h) + boff + n * 2048 + k * 1024); } while (0)
; #define PG8_MMA(ai, bj, At, Bt) do { __builtin_amdgcn_s_setprio(1); _Pragma("unroll") for (int m = 0; m < 4; ++m) _Pragma("unroll") for (int n = 0; n < 2; ++n) _Pragma("unroll") for (int k = 0; k < 2; ++k) \
;         acc[ai][bj][m][n] = __builtin_amdgcn_mfma_f32_16x16x32_bf16(Bt[n][k], At[m][k], acc[ai][bj][m][n], 0, 0, 0); __builtin_amdgcn_s_setprio(0); } while (0)
; #define PG8_WAIT_V(n) asm volatile("s_waitcnt vmcnt(" #n ")" ::: "memory")
; #define PG8_WAIT_L(n) asm volatile("s_waitcnt lgkmcnt(" #n ")" ::: "memory")
; #define PG8_BAR __builtin_amdgcn_s_barrier()
; #define PG8_SCHED __builtin_amdgcn_sched_barrier(0)
; template <class Epi, class Sched>
; __device__ __forceinline__ void gemm_phase(LAS unsigned char* lds, const Gemm g, const Sched& S, const Epi& E) {
;     ...
;             PG8_WAIT_V(8); PG8_WAIT_L(0); PG8_BAR; PG8_MMA(1, 0, At, B0); PG8_MMA(1, 1, At, B1); PG8_BAR; PG8_SCHED;
;             PG8_LDB(B0, 1, 0); PG8_LDB(B1, 1, 1); PG8_SCHED; PG8_LDA(At, 1, 0); PG8_STAGE(PG8_SA(0, 1), a2 + hstepA, voffA);
;             PG8_WAIT_V(8); PG8_WAIT_L(0); PG8_BAR; PG8_MMA(0, 0, At, B0); PG8_MMA(0, 1, At, B1); PG8_BAR; PG8_SCHED;
;             PG8_LDA(At, 1, 1); PG8_STAGE(PG8_SB(1, 0), b3, voffB); PG8_STAGE(PG8_SB(1, 1), b3 + hstepB, voffB); PG8_STAGE(PG8_SA(1, 0), a3, voffA);
	s_waitcnt lgkmcnt(0)
	v_mfma_f32_16x16x32_bf16 v[60:63], v[128:131], v[182:185], v[60:63]
	v_mfma_f32_16x16x32_bf16 v[56:59], v[136:139], v[182:185], v[56:59]
	v_mfma_f32_16x16x32_bf16 v[52:55], v[128:131], v[192:195], v[52:55]
	v_mfma_f32_16x16x32_bf16 v[44:47], v[136:139], v[192:195], v[44:47]
	v_mfma_f32_16x16x32_bf16 v[36:39], v[128:131], v[200:203], v[36:39]
	v_mfma_f32_16x16x32_bf16 v[28:31], v[136:139], v[200:203], v[28:31]
	v_mfma_f32_16x16x32_bf16 v[20:23], v[128:131], v[210:213], v[20:23]
	v_mfma_f32_16x16x32_bf16 v[12:15], v[136:139], v[210:213], v[12:15]
	v_mfma_f32_16x16x32_bf16 v[60:63], v[132:135], v[186:189], v[60:63]
	v_mfma_f32_16x16x32_bf16 v[56:59], v[140:143], v[186:189], v[56:59]
	v_mfma_f32_16x16x32_bf16 v[52:55], v[132:135], v[196:199], v[52:55]
	v_mfma_f32_16x16x32_bf16 v[44:47], v[140:143], v[196:199], v[44:47]
	v_mfma_f32_16x16x32_bf16 v[36:39], v[132:135], v[204:207], v[36:39]
	v_mfma_f32_16x16x32_bf16 v[28:31], v[140:143], v[204:207], v[28:31]
	v_mfma_f32_16x16x32_bf16 v[20:23], v[132:135], v[214:217], v[20:23]
	v_mfma_f32_16x16x32_bf16 v[12:15], v[140:143], v[214:217], v[12:15]
	v_mfma_f32_16x16x32_bf16 v[48:51], v[166:169], v[182:185], v[48:51]
	v_mfma_f32_16x16x32_bf16 v[40:43], v[174:177], v[182:185], v[40:43]
	v_mfma_f32_16x16x32_bf16 v[32:35], v[166:169], v[192:195], v[32:35]
	v_mfma_f32_16x16x32_bf16 v[24:27], v[174:177], v[192:195], v[24:27]
	v_mfma_f32_16x16x32_bf16 v[16:19], v[166:169], v[200:203], v[16:19]
	v_mfma_f32_16x16x32_bf16 v[8:11], v[174:177], v[200:203], v[8:11]
	v_mfma_f32_16x16x32_bf16 v[4:7], v[166:169], v[210:213], v[4:7]
	v_mfma_f32_16x16x32_bf16 v[0:3], v[174:177], v[210:213], v[0:3]
	v_mfma_f32_16x16x32_bf16 v[48:51], v[170:173], v[186:189], v[48:51]
	v_mfma_f32_16x16x32_bf16 v[40:43], v[178:181], v[186:189], v[40:43]
	v_mfma_f32_16x16x32_bf16 v[32:35], v[170:173], v[196:199], v[32:35]
	v_mfma_f32_16x16x32_bf16 v[24:27], v[178:181], v[196:199], v[24:27]
	v_mfma_f32_16x16x32_bf16 v[16:19], v[170:173], v[204:207], v[16:19]
	v_mfma_f32_16x16x32_bf16 v[8:11], v[178:181], v[204:207], v[8:11]
	v_mfma_f32_16x16x32_bf16 v[4:7], v[170:173], v[214:217], v[4:7]
	v_mfma_f32_16x16x32_bf16 v[0:3], v[178:181], v[214:217], v[0:3]
	s_barrier
	s_add_i32 s2, 0, 0x18000
	s_add_i32 s66, 0, 0x1c000
	v_add_u32_e32 v140, s2, v161
	v_add_u32_e32 v178, s66, v161
	ds_read_b128 v[128:131], v140
	ds_read_b128 v[132:135], v140 offset:1024
	ds_read_b128 v[136:139], v140 offset:2048
	ds_read_b128 v[140:143], v140 offset:3072
	ds_read_b128 v[166:169], v178
	ds_read_b128 v[170:173], v178 offset:1024
	ds_read_b128 v[174:177], v178 offset:2048
	ds_read_b128 v[178:181], v178 offset:3072
	s_add_u32 s40, s40, 0x80000
	s_addc_u32 s41, s41, 0
	s_mov_b32 m0, s48
	v_lshl_add_u64 v[226:227], s[40:41], 0, v[144:145]
	ds_read_b128 v[182:185], v165 offset:32768
	ds_read_b128 v[186:189], v165 offset:33792
	ds_read_b128 v[192:195], v165 offset:34816
	ds_read_b128 v[196:199], v165 offset:35840
	ds_read_b128 v[200:203], v165 offset:36864
	ds_read_b128 v[204:207], v165 offset:37888
	ds_read_b128 v[210:213], v165 offset:38912
	ds_read_b128 v[214:217], v165 offset:39936
	global_load_lds_dwordx4 v[226:227], off
	v_lshl_add_u64 v[226:227], s[40:41], 0, v[148:149]
	s_mov_b32 m0, s49
	s_nop 0
	global_load_lds_dwordx4 v[226:227], off
	s_waitcnt vmcnt(8)
	s_waitcnt lgkmcnt(0)
	s_barrier
	s_waitcnt lgkmcnt(0)
	v_mfma_f32_16x16x32_bf16 v[124:127], v[128:131], v[182:185], v[124:127]
	v_mfma_f32_16x16x32_bf16 v[120:123], v[136:139], v[182:185], v[120:123]
	v_mfma_f32_16x16x32_bf16 v[116:119], v[128:131], v[192:195], v[116:119]
	v_mfma_f32_16x16x32_bf16 v[112:115], v[136:139], v[192:195], v[112:115]
	v_mfma_f32_16x16x32_bf16 v[108:111], v[128:131], v[200:203], v[108:111]
	v_mfma_f32_16x16x32_bf16 v[100:103], v[136:139], v[200:203], v[100:103]
	v_mfma_f32_16x16x32_bf16 v[92:95], v[128:131], v[210:213], v[92:95]
	v_mfma_f32_16x16x32_bf16 v[72:75], v[136:139], v[210:213], v[72:75]
	v_mfma_f32_16x16x32_bf16 v[124:127], v[132:135], v[186:189], v[124:127]
	v_mfma_f32_16x16x32_bf16 v[120:123], v[140:143], v[186:189], v[120:123]
	v_mfma_f32_16x16x32_bf16 v[116:119], v[132:135], v[196:199], v[116:119]
	v_mfma_f32_16x16x32_bf16 v[112:115], v[140:143], v[196:199], v[112:115]
	v_mfma_f32_16x16x32_bf16 v[108:111], v[132:135], v[204:207], v[108:111]
	v_mfma_f32_16x16x32_bf16 v[100:103], v[140:143], v[204:207], v[100:103]
	v_mfma_f32_16x16x32_bf16 v[92:95], v[132:135], v[214:217], v[92:95]
	v_mfma_f32_16x16x32_bf16 v[72:75], v[140:143], v[214:217], v[72:75]
	v_mfma_f32_16x16x32_bf16 v[104:107], v[166:169], v[182:185], v[104:107]
	v_mfma_f32_16x16x32_bf16 v[96:99], v[174:177], v[182:185], v[96:99]
	v_mfma_f32_16x16x32_bf16 v[88:91], v[166:169], v[192:195], v[88:91]
	v_mfma_f32_16x16x32_bf16 v[84:87], v[174:177], v[192:195], v[84:87]
	v_mfma_f32_16x16x32_bf16 v[80:83], v[166:169], v[200:203], v[80:83]
	v_mfma_f32_16x16x32_bf16 v[76:79], v[174:177], v[200:203], v[76:79]
	v_mfma_f32_16x16x32_bf16 v[68:71], v[166:169], v[210:213], v[68:71]
	v_mfma_f32_16x16x32_bf16 v[64:67], v[174:177], v[210:213], v[64:67]
	v_mfma_f32_16x16x32_bf16 v[104:107], v[170:173], v[186:189], v[104:107]
	v_mfma_f32_16x16x32_bf16 v[96:99], v[178:181], v[186:189], v[96:99]
	v_mfma_f32_16x16x32_bf16 v[88:91], v[170:173], v[196:199], v[88:91]
	v_mfma_f32_16x16x32_bf16 v[84:87], v[178:181], v[196:199], v[84:87]
	v_mfma_f32_16x16x32_bf16 v[80:83], v[170:173], v[204:207], v[80:83]
	v_mfma_f32_16x16x32_bf16 v[76:79], v[178:181], v[204:207], v[76:79]
	v_mfma_f32_16x16x32_bf16 v[68:71], v[170:173], v[214:217], v[68:71]
	v_mfma_f32_16x16x32_bf16 v[64:67], v[178:181], v[214:217], v[64:67]
	s_barrier
; #define PG8_STAGE(bufoff, gbase, voff) do { _Pragma("unroll") for (int _i = 0; _i < 2; ++_i) \
;         __builtin_amdgcn_global_load_lds((const unsigned*)((const char*)(gbase) + (voff)[_i]), (LAS unsigned*)(lds + (bufoff) + ldsw + _i * 8192), 16, 0, 0); } while (0)
; #define PG8_LDA(dst, b, h) do { _Pragma("unroll") for (int m = 0; m < 4; ++m) _Pragma("unroll") for (int k = 0; k < 2; ++k) dst[m][k] = *(const LAS bf16x8*)(lds + PG8_SA(b, h) + aoff + m * 2048 + k * 1024); } while (0)
; #define PG8_MMA(ai, bj, At, Bt) do { __builtin_amdgcn_s_setprio(1); _Pragma("unroll") for (int m = 0; m < 4; ++m) _Pragma("unroll") for (int n = 0; n < 2; ++n) _Pragma("unroll") for (int k = 0; k < 2; ++k) \
;         acc[ai][bj][m][n] = __builtin_amdgcn_mfma_f32_16x16x32_bf16(Bt[n][k], At[m][k], acc[ai][bj][m][n], 0, 0, 0); __builtin_amdgcn_s_setprio(0); } while (0)
; #define PG8_WAIT_V(n) asm volatile("s_waitcnt vmcnt(" #n ")" ::: "memory")
; #define PG8_WAIT_L(n) asm volatile("s_waitcnt lgkmcnt(" #n ")" ::: "memory")
; #define PG8_BAR __builtin_amdgcn_s_barrier()
; #define PG8_SCHED __builtin_amdgcn_sched_barrier(0)
; template <class Epi, class Sched>
; __device__ __forceinline__ void gemm_phase(LAS unsigned char* lds, const Gemm g, const Sched& S, const Epi& E) {
;     ...
;             PG8_LDA(At, 1, 1); PG8_STAGE(PG8_SB(1, 0), b3, voffB); PG8_STAGE(PG8_SB(1, 1), b3 + hstepB, voffB); PG8_STAGE(PG8_SA(1, 0), a3, voffA);
;             PG8_WAIT_V(8); PG8_WAIT_L(0); PG8_BAR; PG8_MMA(1, 0, At, B0); PG8_MMA(1, 1, At, B1); PG8_BAR; PG8_SCHED;
;         }
;         if (wr == 0) PG8_BAR;
	s_add_i32 s2, s2, s46
	v_lshl_add_u64 v[218:219], v[218:219], 0, s[14:15]
	s_mov_b32 m0, s2
	ds_read_b128 v[182:185], v165 offset:49152
	ds_read_b128 v[186:189], v165 offset:50176
	ds_read_b128 v[192:195], v165 offset:51200
	ds_read_b128 v[196:199], v165 offset:52224
	ds_read_b128 v[200:203], v165 offset:53248
	ds_read_b128 v[204:207], v165 offset:54272
	ds_read_b128 v[210:213], v165 offset:55296
	ds_read_b128 v[214:217], v165 offset:56320
	global_load_lds_dwordx4 v[218:219], off
	s_add_i32 m0, s2, 0x2000
	s_add_u32 s38, s38, 0x80080
	v_lshl_add_u64 v[218:219], v[220:221], 0, s[14:15]
	s_addc_u32 s39, s39, 0
	s_add_i32 s2, s66, s46
	global_load_lds_dwordx4 v[218:219], off
	v_lshl_add_u64 v[218:219], s[38:39], 0, v[146:147]
	s_mov_b32 m0, s2
	s_nop 0
	global_load_lds_dwordx4 v[218:219], off
	v_lshl_add_u64 v[218:219], s[38:39], 0, v[150:151]
	s_add_i32 m0, s2, 0x2000
	s_nop 0
	global_load_lds_dwordx4 v[218:219], off
	v_lshl_add_u64 v[218:219], v[222:223], 0, s[14:15]
	s_mov_b32 m0, s51
	s_nop 0
	global_load_lds_dwordx4 v[218:219], off
	v_lshl_add_u64 v[218:219], v[224:225], 0, s[14:15]
	s_mov_b32 m0, s52
	s_nop 0
	global_load_lds_dwordx4 v[218:219], off
	s_waitcnt vmcnt(8)
	s_waitcnt lgkmcnt(0)
	s_barrier
	s_waitcnt lgkmcnt(0)
	v_mfma_f32_16x16x32_bf16 v[60:63], v[128:131], v[182:185], v[60:63]
	v_mfma_f32_16x16x32_bf16 v[56:59], v[136:139], v[182:185], v[56:59]
	v_mfma_f32_16x16x32_bf16 v[52:55], v[128:131], v[192:195], v[52:55]
	v_mfma_f32_16x16x32_bf16 v[44:47], v[136:139], v[192:195], v[44:47]
	v_mfma_f32_16x16x32_bf16 v[36:39], v[128:131], v[200:203], v[36:39]
	v_mfma_f32_16x16x32_bf16 v[28:31], v[136:139], v[200:203], v[28:31]
	v_mfma_f32_16x16x32_bf16 v[20:23], v[128:131], v[210:213], v[20:23]
	v_mfma_f32_16x16x32_bf16 v[12:15], v[136:139], v[210:213], v[12:15]
	v_mfma_f32_16x16x32_bf16 v[60:63], v[132:135], v[186:189], v[60:63]
	v_mfma_f32_16x16x32_bf16 v[56:59], v[140:143], v[186:189], v[56:59]
	v_mfma_f32_16x16x32_bf16 v[52:55], v[132:135], v[196:199], v[52:55]
	v_mfma_f32_16x16x32_bf16 v[44:47], v[140:143], v[196:199], v[44:47]
	v_mfma_f32_16x16x32_bf16 v[36:39], v[132:135], v[204:207], v[36:39]
	v_mfma_f32_16x16x32_bf16 v[28:31], v[140:143], v[204:207], v[28:31]
	v_mfma_f32_16x16x32_bf16 v[20:23], v[132:135], v[214:217], v[20:23]
	v_mfma_f32_16x16x32_bf16 v[12:15], v[140:143], v[214:217], v[12:15]
	v_mfma_f32_16x16x32_bf16 v[48:51], v[166:169], v[182:185], v[48:51]
	v_mfma_f32_16x16x32_bf16 v[40:43], v[174:177], v[182:185], v[40:43]
	v_mfma_f32_16x16x32_bf16 v[32:35], v[166:169], v[192:195], v[32:35]
	v_mfma_f32_16x16x32_bf16 v[24:27], v[174:177], v[192:195], v[24:27]
	v_mfma_f32_16x16x32_bf16 v[16:19], v[166:169], v[200:203], v[16:19]
	v_mfma_f32_16x16x32_bf16 v[8:11], v[174:177], v[200:203], v[8:11]
	v_mfma_f32_16x16x32_bf16 v[4:7], v[166:169], v[210:213], v[4:7]
	v_mfma_f32_16x16x32_bf16 v[0:3], v[174:177], v[210:213], v[0:3]
	v_mfma_f32_16x16x32_bf16 v[48:51], v[170:173], v[186:189], v[48:51]
	v_mfma_f32_16x16x32_bf16 v[40:43], v[178:181], v[186:189], v[40:43]
	v_mfma_f32_16x16x32_bf16 v[32:35], v[170:173], v[196:199], v[32:35]
	v_mfma_f32_16x16x32_bf16 v[24:27], v[178:181], v[196:199], v[24:27]
	v_mfma_f32_16x16x32_bf16 v[16:19], v[170:173], v[204:207], v[16:19]
	v_mfma_f32_16x16x32_bf16 v[8:11], v[178:181], v[204:207], v[8:11]
	v_mfma_f32_16x16x32_bf16 v[4:7], v[170:173], v[214:217], v[4:7]
	v_mfma_f32_16x16x32_bf16 v[0:3], v[178:181], v[214:217], v[0:3]
	s_barrier
	s_add_i32 s65, s65, 2
	s_add_u32 s36, s36, 0x100
	s_addc_u32 s37, s37, 0
	s_add_u32 s63, s63, 0x100
	s_addc_u32 s64, s64, 0
	s_cmp_gt_u32 s65, 29
	s_cbranch_scc0 .LBB0_807
	s_and_b64 vcc, exec, s[16:17]
	s_cbranch_vccz .LBB0_810
	s_barrier

; #define PG8_STAGE(bufoff, gbase, voff) do { _Pragma("unroll") for (int _i = 0; _i < 2; ++_i) \
;         __builtin_amdgcn_global_load_lds((const unsigned*)((const char*)(gbase) + (voff)[_i]), (LAS unsigned*)(lds + (bufoff) + ldsw + _i * 8192), 16, 0, 0); } while (0)
; #define PG8_LDA(dst, b, h) do { _Pragma("unroll") for (int m = 0; m < 4; ++m) _Pragma("unroll") for (int k = 0; k < 2; ++k) dst[m][k] = *(const LAS bf16x8*)(lds + PG8_SA(b, h) + aoff + m * 2048 + k * 1024); } while (0)
; #define PG8_LDB(dst, b, h) do { _Pragma("unroll") for (int n = 0; n < 2; ++n) _Pragma("unroll") for (int k = 0; k < 2; ++k) dst[n][k] = *(const LAS bf16x8*)(lds + PG8_SB(b, h) + boff + n * 2048 + k * 1024); } while (0)
; #define PG8_MMA(ai, bj, At, Bt) do { __builtin_amdgcn_s_setprio(1); _Pragma("unroll") for (int m = 0; m < 4; ++m) _Pragma("unroll") for (int n = 0; n < 2; ++n) _Pragma("unroll") for (int k = 0; k < 2; ++k) \
;         acc[ai][bj][m][n] = __builtin_amdgcn_mfma_f32_16x16x32_bf16(Bt[n][k], At[m][k], acc[ai][bj][m][n], 0, 0, 0); __builtin_amdgcn_s_setprio(0); } while (0)
; #define PG8_WAIT_V(n) asm volatile("s_waitcnt vmcnt(" #n ")" ::: "memory")
; #define PG8_WAIT_L(n) asm volatile("s_waitcnt lgkmcnt(" #n ")" ::: "memory")
; #define PG8_BAR __builtin_amdgcn_s_barrier()
; #define PG8_SCHED __builtin_amdgcn_sched_barrier(0)
; template <class Epi, class Sched>
; __device__ __forceinline__ void gemm_phase(LAS unsigned char* lds, const Gemm g, const Sched& S, const Epi& E) {
;     ...
;             PG8_LDB(B0, 0, 0); PG8_LDB(B1, 0, 1); PG8_SCHED; PG8_LDA(At, 0, 0); PG8_STAGE(PG8_SA(1, 1), a1 + hstepA, voffA);
;             PG8_WAIT_V(8); PG8_WAIT_L(0); PG8_BAR; PG8_MMA(0, 0, At, B0); PG8_MMA(0, 1, At, B1); PG8_BAR; PG8_SCHED;
;             PG8_LDA(At, 0, 1); PG8_STAGE(PG8_SB(0, 0), b2, voffB); PG8_STAGE(PG8_SB(0, 1), b2 + hstepB, voffB); PG8_STAGE(PG8_SA(0, 0), a2, voffA);
;             PG8_WAIT_V(8); PG8_WAIT_L(0); PG8_BAR; PG8_MMA(1, 0, At, B0); PG8_MMA(1, 1, At, B1); PG8_BAR; PG8_SCHED;
.LBB0_928:
	ds_read_b128 v[126:129], v222
	ds_read_b128 v[130:133], v222 offset:1024
	ds_read_b128 v[134:137], v222 offset:2048
	ds_read_b128 v[138:141], v222 offset:3072
	ds_read_b128 v[142:145], v223
	ds_read_b128 v[146:149], v223 offset:1024
	ds_read_b128 v[150:153], v223 offset:2048
	ds_read_b128 v[154:157], v223 offset:3072
	s_add_u32 s2, s6, 0xfff80080
	s_addc_u32 s8, s7, -1
	s_cmp_eq_u32 s79, 28
	s_cselect_b32 s55, s33, s8
	s_cselect_b32 s54, s47, s2
	s_cselect_b32 s9, s45, s78
	s_cselect_b32 s8, s53, s77
	v_lshl_add_u64 v[112:113], s[6:7], 0, v[196:197]
	s_add_i32 m0, s62, 0xc000
	ds_read_b128 v[164:167], v224
	ds_read_b128 v[168:171], v224 offset:1024
	ds_read_b128 v[172:175], v224 offset:2048
	ds_read_b128 v[176:179], v224 offset:3072
	ds_read_b128 v[204:207], v224 offset:4096
	ds_read_b128 v[226:229], v224 offset:5120
	ds_read_b128 v[230:233], v224 offset:6144
	ds_read_b128 v[234:237], v224 offset:7168
	global_load_lds_dwordx4 v[112:113], off
	v_lshl_add_u64 v[112:113], s[6:7], 0, v[198:199]
	s_add_i32 m0, s62, 0xe000
	s_nop 0
	global_load_lds_dwordx4 v[112:113], off
	s_waitcnt vmcnt(8)
	s_waitcnt lgkmcnt(0)
	s_barrier
	s_waitcnt lgkmcnt(0)
	v_mfma_f32_16x16x32_bf16 v[158:161], v[126:129], v[164:167], v[160:163]
	v_mfma_f32_16x16x32_bf16 v[60:63], v[134:137], v[164:167], v[60:63]
	v_mfma_f32_16x16x32_bf16 v[122:125], v[126:129], v[172:175], v[122:125]
	v_mfma_f32_16x16x32_bf16 v[52:55], v[134:137], v[172:175], v[52:55]
	v_mfma_f32_16x16x32_bf16 v[108:111], v[126:129], v[204:207], v[108:111]
	v_mfma_f32_16x16x32_bf16 v[44:47], v[134:137], v[204:207], v[44:47]
	v_mfma_f32_16x16x32_bf16 v[104:107], v[126:129], v[230:233], v[104:107]
	v_mfma_f32_16x16x32_bf16 v[40:43], v[134:137], v[230:233], v[40:43]
	v_mfma_f32_16x16x32_bf16 v[158:161], v[130:133], v[168:171], v[158:161]
	v_mfma_f32_16x16x32_bf16 v[60:63], v[138:141], v[168:171], v[60:63]
	v_mfma_f32_16x16x32_bf16 v[122:125], v[130:133], v[176:179], v[122:125]
	v_mfma_f32_16x16x32_bf16 v[52:55], v[138:141], v[176:179], v[52:55]
	v_mfma_f32_16x16x32_bf16 v[108:111], v[130:133], v[226:229], v[108:111]
	v_mfma_f32_16x16x32_bf16 v[44:47], v[138:141], v[226:229], v[44:47]
	v_mfma_f32_16x16x32_bf16 v[104:107], v[130:133], v[234:237], v[104:107]
	v_mfma_f32_16x16x32_bf16 v[40:43], v[138:141], v[234:237], v[40:43]
	v_mfma_f32_16x16x32_bf16 v[112:115], v[142:145], v[164:167], v[114:117]
	v_mfma_f32_16x16x32_bf16 v[56:59], v[150:153], v[164:167], v[56:59]
	v_mfma_f32_16x16x32_bf16 v[116:119], v[142:145], v[172:175], v[118:121]
	v_mfma_f32_16x16x32_bf16 v[48:51], v[150:153], v[172:175], v[48:51]
	v_mfma_f32_16x16x32_bf16 v[100:103], v[142:145], v[204:207], v[100:103]
	v_mfma_f32_16x16x32_bf16 v[36:39], v[150:153], v[204:207], v[36:39]
	v_mfma_f32_16x16x32_bf16 v[96:99], v[142:145], v[230:233], v[96:99]
	v_mfma_f32_16x16x32_bf16 v[32:35], v[150:153], v[230:233], v[32:35]
	v_mfma_f32_16x16x32_bf16 v[112:115], v[146:149], v[168:171], v[112:115]
	v_mfma_f32_16x16x32_bf16 v[56:59], v[154:157], v[168:171], v[56:59]
	v_mfma_f32_16x16x32_bf16 v[118:121], v[146:149], v[176:179], v[116:119]
	v_mfma_f32_16x16x32_bf16 v[48:51], v[154:157], v[176:179], v[48:51]
	v_mfma_f32_16x16x32_bf16 v[100:103], v[146:149], v[226:229], v[100:103]
	v_mfma_f32_16x16x32_bf16 v[36:39], v[154:157], v[226:229], v[36:39]
	v_mfma_f32_16x16x32_bf16 v[96:99], v[146:149], v[234:237], v[96:99]
	v_mfma_f32_16x16x32_bf16 v[32:35], v[154:157], v[234:237], v[32:35]
	s_barrier
	s_add_i32 s2, s71, s59
	v_lshl_add_u64 v[210:211], s[8:9], 0, v[184:185]
	s_mov_b32 m0, s2
	ds_read_b128 v[162:165], v224 offset:16384
	ds_read_b128 v[166:169], v224 offset:17408
	ds_read_b128 v[170:173], v224 offset:18432
	ds_read_b128 v[174:177], v224 offset:19456
	ds_read_b128 v[204:207], v224 offset:20480
	ds_read_b128 v[226:229], v224 offset:21504
	ds_read_b128 v[230:233], v224 offset:22528
	ds_read_b128 v[234:237], v224 offset:23552
	global_load_lds_dwordx4 v[210:211], off
	s_add_i32 m0, s2, 0x2000
	s_add_u32 s80, s8, 0x80000
	v_lshl_add_u64 v[238:239], s[8:9], 0, v[180:181]
	s_addc_u32 s81, s9, 0
	s_add_i32 s2, s73, s59
	global_load_lds_dwordx4 v[238:239], off
	v_lshl_add_u64 v[116:117], s[80:81], 0, v[184:185]
	s_mov_b32 m0, s2
	v_lshl_add_u64 v[240:241], s[54:55], 0, v[186:187]
	global_load_lds_dwordx4 v[116:117], off
	v_lshl_add_u64 v[116:117], s[80:81], 0, v[180:181]
	s_add_i32 m0, s2, 0x2000
	v_lshl_add_u64 v[242:243], s[54:55], 0, v[182:183]
	global_load_lds_dwordx4 v[116:117], off
	s_mov_b32 m0, s62
	s_nop 0
	global_load_lds_dwordx4 v[240:241], off
	s_mov_b32 m0, s63
	s_nop 0
	global_load_lds_dwordx4 v[242:243], off
	s_waitcnt vmcnt(8)
	s_waitcnt lgkmcnt(0)
	s_barrier
; #define PG8_STAGE(bufoff, gbase, voff) do { _Pragma("unroll") for (int _i = 0; _i < 2; ++_i) \
;         __builtin_amdgcn_global_load_lds((const unsigned*)((const char*)(gbase) + (voff)[_i]), (LAS unsigned*)(lds + (bufoff) + ldsw + _i * 8192), 16, 0, 0); } while (0)
; #define PG8_LDA(dst, b, h) do { _Pragma("unroll") for (int m = 0; m < 4; ++m) _Pragma("unroll") for (int k = 0; k < 2; ++k) dst[m][k] = *(const LAS bf16x8*)(lds + PG8_SA(b, h) + aoff + m * 2048 + k * 1024); } while (0)
; #define PG8_LDB(dst, b, h) do { _Pragma("unroll") for (int n = 0; n < 2; ++n) _Pragma("unroll") for (int k = 0; k < 2; ++k) dst[n][k] = *(const LAS bf16x8*)(lds + PG8_SB(b, h) + boff + n * 2048 + k * 1024); } while (0)
; #define PG8_MMA(ai, bj, At, Bt) do { __builtin_amdgcn_s_setprio(1); _Pragma("unroll") for (int m = 0; m < 4; ++m) _Pragma("unroll") for (int n = 0; n < 2; ++n) _Pragma("unroll") for (int k = 0; k < 2; ++k) \
;         acc[ai][bj][m][n] = __builtin_amdgcn_mfma_f32_16x16x32_bf16(Bt[n][k], At[m][k], acc[ai][bj][m][n], 0, 0, 0); __builtin_amdgcn_s_setprio(0); } while (0)
; #define PG8_WAIT_V(n) asm volatile("s_waitcnt vmcnt(" #n ")" ::: "memory")
; #define PG8_WAIT_L(n) asm volatile("s_waitcnt lgkmcnt(" #n ")" ::: "memory")
; #define PG8_BAR __builtin_amdgcn_s_barrier()
; #define PG8_SCHED __builtin_amdgcn_sched_barrier(0)
; template <class Epi, class Sched>
; __device__ __forceinline__ void gemm_phase(LAS unsigned char* lds, const Gemm g, const Sched& S, const Epi& E) {
;     ...
;             PG8_WAIT_V(8); PG8_WAIT_L(0); PG8_BAR; PG8_MMA(1, 0, At, B0); PG8_MMA(1, 1, At, B1); PG8_BAR; PG8_SCHED;
;             PG8_LDB(B0, 1, 0); PG8_LDB(B1, 1, 1); PG8_SCHED; PG8_LDA(At, 1, 0); PG8_STAGE(PG8_SA(0, 1), a2 + hstepA, voffA);
;             PG8_WAIT_V(8); PG8_WAIT_L(0); PG8_BAR; PG8_MMA(0, 0, At, B0); PG8_MMA(0, 1, At, B1); PG8_BAR; PG8_SCHED;
;             PG8_LDA(At, 1, 1); PG8_STAGE(PG8_SB(1, 0), b3, voffB); PG8_STAGE(PG8_SB(1, 1), b3 + hstepB, voffB); PG8_STAGE(PG8_SA(1, 0), a3, voffA);
	s_waitcnt lgkmcnt(0)
	v_mfma_f32_16x16x32_bf16 v[92:95], v[126:129], v[162:165], v[92:95]
	v_mfma_f32_16x16x32_bf16 v[28:31], v[134:137], v[162:165], v[28:31]
	v_mfma_f32_16x16x32_bf16 v[84:87], v[126:129], v[170:173], v[84:87]
	v_mfma_f32_16x16x32_bf16 v[20:23], v[134:137], v[170:173], v[20:23]
	v_mfma_f32_16x16x32_bf16 v[76:79], v[126:129], v[204:207], v[76:79]
	v_mfma_f32_16x16x32_bf16 v[12:15], v[134:137], v[204:207], v[12:15]
	v_mfma_f32_16x16x32_bf16 v[72:75], v[126:129], v[230:233], v[72:75]
	v_mfma_f32_16x16x32_bf16 v[8:11], v[134:137], v[230:233], v[8:11]
	v_mfma_f32_16x16x32_bf16 v[92:95], v[130:133], v[166:169], v[92:95]
	v_mfma_f32_16x16x32_bf16 v[28:31], v[138:141], v[166:169], v[28:31]
	v_mfma_f32_16x16x32_bf16 v[84:87], v[130:133], v[174:177], v[84:87]
	v_mfma_f32_16x16x32_bf16 v[20:23], v[138:141], v[174:177], v[20:23]
	v_mfma_f32_16x16x32_bf16 v[76:79], v[130:133], v[226:229], v[76:79]
	v_mfma_f32_16x16x32_bf16 v[12:15], v[138:141], v[226:229], v[12:15]
	v_mfma_f32_16x16x32_bf16 v[72:75], v[130:133], v[234:237], v[72:75]
	v_mfma_f32_16x16x32_bf16 v[8:11], v[138:141], v[234:237], v[8:11]
	v_mfma_f32_16x16x32_bf16 v[88:91], v[142:145], v[162:165], v[88:91]
	v_mfma_f32_16x16x32_bf16 v[24:27], v[150:153], v[162:165], v[24:27]
	v_mfma_f32_16x16x32_bf16 v[80:83], v[142:145], v[170:173], v[80:83]
	v_mfma_f32_16x16x32_bf16 v[16:19], v[150:153], v[170:173], v[16:19]
	v_mfma_f32_16x16x32_bf16 v[68:71], v[142:145], v[204:207], v[68:71]
	v_mfma_f32_16x16x32_bf16 v[4:7], v[150:153], v[204:207], v[4:7]
	v_mfma_f32_16x16x32_bf16 v[64:67], v[142:145], v[230:233], v[64:67]
	v_mfma_f32_16x16x32_bf16 v[0:3], v[150:153], v[230:233], v[0:3]
	v_mfma_f32_16x16x32_bf16 v[88:91], v[146:149], v[166:169], v[88:91]
	v_mfma_f32_16x16x32_bf16 v[24:27], v[154:157], v[166:169], v[24:27]
	v_mfma_f32_16x16x32_bf16 v[80:83], v[146:149], v[174:177], v[80:83]
	v_mfma_f32_16x16x32_bf16 v[16:19], v[154:157], v[174:177], v[16:19]
	v_mfma_f32_16x16x32_bf16 v[68:71], v[146:149], v[226:229], v[68:71]
	v_mfma_f32_16x16x32_bf16 v[4:7], v[154:157], v[226:229], v[4:7]
	v_mfma_f32_16x16x32_bf16 v[64:67], v[146:149], v[234:237], v[64:67]
	v_mfma_f32_16x16x32_bf16 v[0:3], v[154:157], v[234:237], v[0:3]
	s_barrier
	s_add_i32 s2, 0, 0x18000
	v_add_u32_e32 v116, s2, v212
	s_add_i32 s72, 0, 0x1c000
	ds_read_b128 v[126:129], v116
	ds_read_b128 v[130:133], v116 offset:1024
	ds_read_b128 v[134:137], v116 offset:2048
	ds_read_b128 v[138:141], v116 offset:3072
	v_add_u32_e32 v116, s72, v212
	ds_read_b128 v[142:145], v116
	ds_read_b128 v[146:149], v116 offset:1024
	ds_read_b128 v[150:153], v116 offset:2048
	ds_read_b128 v[154:157], v116 offset:3072
	s_add_u32 s54, s54, 0x80000
	s_addc_u32 s55, s55, 0
	s_mov_b32 m0, s64
	v_lshl_add_u64 v[116:117], s[54:55], 0, v[186:187]
	ds_read_b128 v[164:167], v224 offset:32768
	ds_read_b128 v[168:171], v224 offset:33792
	ds_read_b128 v[172:175], v224 offset:34816
	ds_read_b128 v[176:179], v224 offset:35840
	ds_read_b128 v[204:207], v224 offset:36864
	ds_read_b128 v[226:229], v224 offset:37888
	ds_read_b128 v[230:233], v224 offset:38912
	ds_read_b128 v[234:237], v224 offset:39936
	global_load_lds_dwordx4 v[116:117], off
	v_lshl_add_u64 v[116:117], s[54:55], 0, v[182:183]
	s_mov_b32 m0, s65
	s_nop 0
	global_load_lds_dwordx4 v[116:117], off
	s_waitcnt vmcnt(8)
	s_waitcnt lgkmcnt(0)
	s_barrier
	s_waitcnt lgkmcnt(0)
	v_mfma_f32_16x16x32_bf16 v[158:161], v[126:129], v[164:167], v[158:161]
	v_mfma_f32_16x16x32_bf16 v[60:63], v[134:137], v[164:167], v[60:63]
	v_mfma_f32_16x16x32_bf16 v[122:125], v[126:129], v[172:175], v[122:125]
	v_mfma_f32_16x16x32_bf16 v[52:55], v[134:137], v[172:175], v[52:55]
	v_mfma_f32_16x16x32_bf16 v[108:111], v[126:129], v[204:207], v[108:111]
	v_mfma_f32_16x16x32_bf16 v[44:47], v[134:137], v[204:207], v[44:47]
	v_mfma_f32_16x16x32_bf16 v[104:107], v[126:129], v[230:233], v[104:107]
	v_mfma_f32_16x16x32_bf16 v[40:43], v[134:137], v[230:233], v[40:43]
	v_mfma_f32_16x16x32_bf16 v[160:163], v[130:133], v[168:171], v[158:161]
	v_mfma_f32_16x16x32_bf16 v[60:63], v[138:141], v[168:171], v[60:63]
	v_mfma_f32_16x16x32_bf16 v[122:125], v[130:133], v[176:179], v[122:125]
	v_mfma_f32_16x16x32_bf16 v[52:55], v[138:141], v[176:179], v[52:55]
	v_mfma_f32_16x16x32_bf16 v[108:111], v[130:133], v[226:229], v[108:111]
	v_mfma_f32_16x16x32_bf16 v[44:47], v[138:141], v[226:229], v[44:47]
	v_mfma_f32_16x16x32_bf16 v[104:107], v[130:133], v[234:237], v[104:107]
	v_mfma_f32_16x16x32_bf16 v[40:43], v[138:141], v[234:237], v[40:43]
	v_mfma_f32_16x16x32_bf16 v[112:115], v[142:145], v[164:167], v[112:115]
	v_mfma_f32_16x16x32_bf16 v[56:59], v[150:153], v[164:167], v[56:59]
	v_mfma_f32_16x16x32_bf16 v[118:121], v[142:145], v[172:175], v[118:121]
	v_mfma_f32_16x16x32_bf16 v[48:51], v[150:153], v[172:175], v[48:51]
	v_mfma_f32_16x16x32_bf16 v[100:103], v[142:145], v[204:207], v[100:103]
	v_mfma_f32_16x16x32_bf16 v[36:39], v[150:153], v[204:207], v[36:39]
	v_mfma_f32_16x16x32_bf16 v[96:99], v[142:145], v[230:233], v[96:99]
	v_mfma_f32_16x16x32_bf16 v[32:35], v[150:153], v[230:233], v[32:35]
	v_mfma_f32_16x16x32_bf16 v[114:117], v[146:149], v[168:171], v[112:115]
	v_mfma_f32_16x16x32_bf16 v[56:59], v[154:157], v[168:171], v[56:59]
	v_mfma_f32_16x16x32_bf16 v[118:121], v[146:149], v[176:179], v[118:121]
	v_mfma_f32_16x16x32_bf16 v[48:51], v[154:157], v[176:179], v[48:51]
	v_mfma_f32_16x16x32_bf16 v[100:103], v[146:149], v[226:229], v[100:103]
	v_mfma_f32_16x16x32_bf16 v[36:39], v[154:157], v[226:229], v[36:39]
	v_mfma_f32_16x16x32_bf16 v[96:99], v[146:149], v[234:237], v[96:99]
	v_mfma_f32_16x16x32_bf16 v[32:35], v[154:157], v[234:237], v[32:35]
	s_barrier
; #define PG8_STAGE(bufoff, gbase, voff) do { _Pragma("unroll") for (int _i = 0; _i < 2; ++_i) \
;         __builtin_amdgcn_global_load_lds((const unsigned*)((const char*)(gbase) + (voff)[_i]), (LAS unsigned*)(lds + (bufoff) + ldsw + _i * 8192), 16, 0, 0); } while (0)
; #define PG8_LDA(dst, b, h) do { _Pragma("unroll") for (int m = 0; m < 4; ++m) _Pragma("unroll") for (int k = 0; k < 2; ++k) dst[m][k] = *(const LAS bf16x8*)(lds + PG8_SA(b, h) + aoff + m * 2048 + k * 1024); } while (0)
; #define PG8_MMA(ai, bj, At, Bt) do { __builtin_amdgcn_s_setprio(1); _Pragma("unroll") for (int m = 0; m < 4; ++m) _Pragma("unroll") for (int n = 0; n < 2; ++n) _Pragma("unroll") for (int k = 0; k < 2; ++k) \
;         acc[ai][bj][m][n] = __builtin_amdgcn_mfma_f32_16x16x32_bf16(Bt[n][k], At[m][k], acc[ai][bj][m][n], 0, 0, 0); __builtin_amdgcn_s_setprio(0); } while (0)
; #define PG8_WAIT_V(n) asm volatile("s_waitcnt vmcnt(" #n ")" ::: "memory")
; #define PG8_WAIT_L(n) asm volatile("s_waitcnt lgkmcnt(" #n ")" ::: "memory")
; #define PG8_BAR __builtin_amdgcn_s_barrier()
; #define PG8_SCHED __builtin_amdgcn_sched_barrier(0)
; template <class Epi, class Sched>
; __device__ __forceinline__ void gemm_phase(LAS unsigned char* lds, const Gemm g, const Sched& S, const Epi& E) {
;     ...
;             PG8_LDA(At, 1, 1); PG8_STAGE(PG8_SB(1, 0), b3, voffB); PG8_STAGE(PG8_SB(1, 1), b3 + hstepB, voffB); PG8_STAGE(PG8_SA(1, 0), a3, voffA);
;             PG8_WAIT_V(8); PG8_WAIT_L(0); PG8_BAR; PG8_MMA(1, 0, At, B0); PG8_MMA(1, 1, At, B1); PG8_BAR; PG8_SCHED;
;         }
;         if (wr == 0) PG8_BAR;
	s_add_i32 s2, s2, s59
	v_lshl_add_u64 v[112:113], v[210:211], 0, s[20:21]
	s_mov_b32 m0, s2
	ds_read_b128 v[164:167], v224 offset:49152
	ds_read_b128 v[168:171], v224 offset:50176
	ds_read_b128 v[172:175], v224 offset:51200
	ds_read_b128 v[176:179], v224 offset:52224
	ds_read_b128 v[204:207], v224 offset:53248
	ds_read_b128 v[226:229], v224 offset:54272
	ds_read_b128 v[230:233], v224 offset:55296
	ds_read_b128 v[234:237], v224 offset:56320
	global_load_lds_dwordx4 v[112:113], off
	s_add_i32 m0, s2, 0x2000
	s_add_u32 s8, s8, 0x80080
	v_lshl_add_u64 v[112:113], v[238:239], 0, s[20:21]
	s_addc_u32 s9, s9, 0
	s_add_i32 s2, s72, s59
	global_load_lds_dwordx4 v[112:113], off
	v_lshl_add_u64 v[112:113], s[8:9], 0, v[184:185]
	s_mov_b32 m0, s2
	s_nop 0
	global_load_lds_dwordx4 v[112:113], off
	v_lshl_add_u64 v[112:113], s[8:9], 0, v[180:181]
	s_add_i32 m0, s2, 0x2000
	s_nop 0
	global_load_lds_dwordx4 v[112:113], off
	v_lshl_add_u64 v[112:113], v[240:241], 0, s[20:21]
	s_mov_b32 m0, s67
	s_nop 0
	global_load_lds_dwordx4 v[112:113], off
	v_lshl_add_u64 v[112:113], v[242:243], 0, s[20:21]
	s_mov_b32 m0, s68
	s_nop 0
	global_load_lds_dwordx4 v[112:113], off
	s_waitcnt vmcnt(8)
	s_waitcnt lgkmcnt(0)
	s_barrier
	s_waitcnt lgkmcnt(0)
	v_mfma_f32_16x16x32_bf16 v[92:95], v[126:129], v[164:167], v[92:95]
	v_mfma_f32_16x16x32_bf16 v[28:31], v[134:137], v[164:167], v[28:31]
	v_mfma_f32_16x16x32_bf16 v[84:87], v[126:129], v[172:175], v[84:87]
	v_mfma_f32_16x16x32_bf16 v[20:23], v[134:137], v[172:175], v[20:23]
	v_mfma_f32_16x16x32_bf16 v[76:79], v[126:129], v[204:207], v[76:79]
	v_mfma_f32_16x16x32_bf16 v[12:15], v[134:137], v[204:207], v[12:15]
	v_mfma_f32_16x16x32_bf16 v[72:75], v[126:129], v[230:233], v[72:75]
	v_mfma_f32_16x16x32_bf16 v[8:11], v[134:137], v[230:233], v[8:11]
	v_mfma_f32_16x16x32_bf16 v[92:95], v[130:133], v[168:171], v[92:95]
	v_mfma_f32_16x16x32_bf16 v[28:31], v[138:141], v[168:171], v[28:31]
	v_mfma_f32_16x16x32_bf16 v[84:87], v[130:133], v[176:179], v[84:87]
	v_mfma_f32_16x16x32_bf16 v[20:23], v[138:141], v[176:179], v[20:23]
	v_mfma_f32_16x16x32_bf16 v[76:79], v[130:133], v[226:229], v[76:79]
	v_mfma_f32_16x16x32_bf16 v[12:15], v[138:141], v[226:229], v[12:15]
	v_mfma_f32_16x16x32_bf16 v[72:75], v[130:133], v[234:237], v[72:75]
	v_mfma_f32_16x16x32_bf16 v[8:11], v[138:141], v[234:237], v[8:11]
	v_mfma_f32_16x16x32_bf16 v[88:91], v[142:145], v[164:167], v[88:91]
	v_mfma_f32_16x16x32_bf16 v[24:27], v[150:153], v[164:167], v[24:27]
	v_mfma_f32_16x16x32_bf16 v[80:83], v[142:145], v[172:175], v[80:83]
	v_mfma_f32_16x16x32_bf16 v[16:19], v[150:153], v[172:175], v[16:19]
	v_mfma_f32_16x16x32_bf16 v[68:71], v[142:145], v[204:207], v[68:71]
	v_mfma_f32_16x16x32_bf16 v[4:7], v[150:153], v[204:207], v[4:7]
	v_mfma_f32_16x16x32_bf16 v[64:67], v[142:145], v[230:233], v[64:67]
	v_mfma_f32_16x16x32_bf16 v[0:3], v[150:153], v[230:233], v[0:3]
	v_mfma_f32_16x16x32_bf16 v[88:91], v[146:149], v[168:171], v[88:91]
	v_mfma_f32_16x16x32_bf16 v[24:27], v[154:157], v[168:171], v[24:27]
	v_mfma_f32_16x16x32_bf16 v[80:83], v[146:149], v[176:179], v[80:83]
	v_mfma_f32_16x16x32_bf16 v[16:19], v[154:157], v[176:179], v[16:19]
	v_mfma_f32_16x16x32_bf16 v[68:71], v[146:149], v[226:229], v[68:71]
	v_mfma_f32_16x16x32_bf16 v[4:7], v[154:157], v[226:229], v[4:7]
	v_mfma_f32_16x16x32_bf16 v[64:67], v[146:149], v[234:237], v[64:67]
	v_mfma_f32_16x16x32_bf16 v[0:3], v[154:157], v[234:237], v[0:3]
	s_barrier
	s_add_i32 s79, s79, 2
	s_add_u32 s6, s6, 0x100
	s_addc_u32 s7, s7, 0
	s_add_u32 s77, s77, 0x100
	s_addc_u32 s78, s78, 0
	s_cmp_gt_u32 s79, 29
	s_cbranch_scc0 .LBB0_928
	s_and_b64 vcc, exec, s[22:23]
	s_cbranch_vccz .LBB0_931
	s_barrier

; #define PG8_STAGE(bufoff, gbase, voff) do { _Pragma("unroll") for (int _i = 0; _i < 2; ++_i) \
;         __builtin_amdgcn_global_load_lds((const unsigned*)((const char*)(gbase) + (voff)[_i]), (LAS unsigned*)(lds + (bufoff) + ldsw + _i * 8192), 16, 0, 0); } while (0)
; #define PG8_LDA(dst, b, h) do { _Pragma("unroll") for (int m = 0; m < 4; ++m) _Pragma("unroll") for (int k = 0; k < 2; ++k) dst[m][k] = *(const LAS bf16x8*)(lds + PG8_SA(b, h) + aoff + m * 2048 + k * 1024); } while (0)
; #define PG8_LDB(dst, b, h) do { _Pragma("unroll") for (int n = 0; n < 2; ++n) _Pragma("unroll") for (int k = 0; k < 2; ++k) dst[n][k] = *(const LAS bf16x8*)(lds + PG8_SB(b, h) + boff + n * 2048 + k * 1024); } while (0)
; #define PG8_MMA(ai, bj, At, Bt) do { __builtin_amdgcn_s_setprio(1); _Pragma("unroll") for (int m = 0; m < 4; ++m) _Pragma("unroll") for (int n = 0; n < 2; ++n) _Pragma("unroll") for (int k = 0; k < 2; ++k) \
;         acc[ai][bj][m][n] = __builtin_amdgcn_mfma_f32_16x16x32_bf16(Bt[n][k], At[m][k], acc[ai][bj][m][n], 0, 0, 0); __builtin_amdgcn_s_setprio(0); } while (0)
; #define PG8_WAIT_V(n) asm volatile("s_waitcnt vmcnt(" #n ")" ::: "memory")
; #define PG8_WAIT_L(n) asm volatile("s_waitcnt lgkmcnt(" #n ")" ::: "memory")
; #define PG8_BAR __builtin_amdgcn_s_barrier()
; #define PG8_SCHED __builtin_amdgcn_sched_barrier(0)
; template <class Epi, class Sched>
; __device__ __forceinline__ void gemm_phase(LAS unsigned char* lds, const Gemm g, const Sched& S, const Epi& E) {
;     ...
;             PG8_LDB(B0, 0, 0); PG8_LDB(B1, 0, 1); PG8_SCHED; PG8_LDA(At, 0, 0); PG8_STAGE(PG8_SA(1, 1), a1 + hstepA, voffA);
;             PG8_WAIT_V(8); PG8_WAIT_L(0); PG8_BAR; PG8_MMA(0, 0, At, B0); PG8_MMA(0, 1, At, B1); PG8_BAR; PG8_SCHED;
;             PG8_LDA(At, 0, 1); PG8_STAGE(PG8_SB(0, 0), b2, voffB); PG8_STAGE(PG8_SB(0, 1), b2 + hstepB, voffB); PG8_STAGE(PG8_SA(0, 0), a2, voffA);
;             PG8_WAIT_V(8); PG8_WAIT_L(0); PG8_BAR; PG8_MMA(1, 0, At, B0); PG8_MMA(1, 1, At, B1); PG8_BAR; PG8_SCHED;
.LBB0_1075:
	ds_read_b128 v[128:131], v163
	ds_read_b128 v[132:135], v163 offset:1024
	ds_read_b128 v[136:139], v163 offset:2048
	ds_read_b128 v[140:143], v163 offset:3072
	ds_read_b128 v[166:169], v164
	ds_read_b128 v[170:173], v164 offset:1024
	ds_read_b128 v[174:177], v164 offset:2048
	ds_read_b128 v[178:181], v164 offset:3072
	s_add_u32 s2, s28, 0xffea0080
	s_addc_u32 s30, s29, -1
	s_cmpk_eq_i32 s61, 0x54
	s_cselect_b32 s35, s5, s30
	s_cselect_b32 s34, s4, s2
	s_cselect_b32 s31, s27, s60
	s_cselect_b32 s30, s26, s33
	v_lshl_add_u64 v[206:207], s[28:29], 0, v[152:153]
	s_add_i32 m0, s41, 0xc000
	ds_read_b128 v[182:185], v165
	ds_read_b128 v[186:189], v165 offset:1024
	ds_read_b128 v[190:193], v165 offset:2048
	ds_read_b128 v[194:197], v165 offset:3072
	ds_read_b128 v[198:201], v165 offset:4096
	ds_read_b128 v[202:205], v165 offset:5120
	ds_read_b128 v[210:213], v165 offset:6144
	ds_read_b128 v[214:217], v165 offset:7168
	global_load_lds_dwordx4 v[206:207], off
	v_lshl_add_u64 v[206:207], s[28:29], 0, v[154:155]
	s_add_i32 m0, s41, 0xe000
	s_nop 0
	global_load_lds_dwordx4 v[206:207], off
	s_waitcnt vmcnt(8)
	s_waitcnt lgkmcnt(0)
	s_barrier
	s_waitcnt lgkmcnt(0)
	v_mfma_f32_16x16x32_bf16 v[124:127], v[128:131], v[182:185], v[124:127]
	v_mfma_f32_16x16x32_bf16 v[120:123], v[136:139], v[182:185], v[120:123]
	v_mfma_f32_16x16x32_bf16 v[116:119], v[128:131], v[190:193], v[116:119]
	v_mfma_f32_16x16x32_bf16 v[112:115], v[136:139], v[190:193], v[112:115]
	v_mfma_f32_16x16x32_bf16 v[108:111], v[128:131], v[198:201], v[108:111]
	v_mfma_f32_16x16x32_bf16 v[100:103], v[136:139], v[198:201], v[100:103]
	v_mfma_f32_16x16x32_bf16 v[92:95], v[128:131], v[210:213], v[92:95]
	v_mfma_f32_16x16x32_bf16 v[72:75], v[136:139], v[210:213], v[72:75]
	v_mfma_f32_16x16x32_bf16 v[124:127], v[132:135], v[186:189], v[124:127]
	v_mfma_f32_16x16x32_bf16 v[120:123], v[140:143], v[186:189], v[120:123]
	v_mfma_f32_16x16x32_bf16 v[116:119], v[132:135], v[194:197], v[116:119]
	v_mfma_f32_16x16x32_bf16 v[112:115], v[140:143], v[194:197], v[112:115]
	v_mfma_f32_16x16x32_bf16 v[108:111], v[132:135], v[202:205], v[108:111]
	v_mfma_f32_16x16x32_bf16 v[100:103], v[140:143], v[202:205], v[100:103]
	v_mfma_f32_16x16x32_bf16 v[92:95], v[132:135], v[214:217], v[92:95]
	v_mfma_f32_16x16x32_bf16 v[72:75], v[140:143], v[214:217], v[72:75]
	v_mfma_f32_16x16x32_bf16 v[104:107], v[166:169], v[182:185], v[104:107]
	v_mfma_f32_16x16x32_bf16 v[96:99], v[174:177], v[182:185], v[96:99]
	v_mfma_f32_16x16x32_bf16 v[88:91], v[166:169], v[190:193], v[88:91]
	v_mfma_f32_16x16x32_bf16 v[84:87], v[174:177], v[190:193], v[84:87]
	v_mfma_f32_16x16x32_bf16 v[80:83], v[166:169], v[198:201], v[80:83]
	v_mfma_f32_16x16x32_bf16 v[76:79], v[174:177], v[198:201], v[76:79]
	v_mfma_f32_16x16x32_bf16 v[68:71], v[166:169], v[210:213], v[68:71]
	v_mfma_f32_16x16x32_bf16 v[64:67], v[174:177], v[210:213], v[64:67]
	v_mfma_f32_16x16x32_bf16 v[104:107], v[170:173], v[186:189], v[104:107]
	v_mfma_f32_16x16x32_bf16 v[96:99], v[178:181], v[186:189], v[96:99]
	v_mfma_f32_16x16x32_bf16 v[88:91], v[170:173], v[194:197], v[88:91]
	v_mfma_f32_16x16x32_bf16 v[84:87], v[178:181], v[194:197], v[84:87]
	v_mfma_f32_16x16x32_bf16 v[80:83], v[170:173], v[202:205], v[80:83]
	v_mfma_f32_16x16x32_bf16 v[76:79], v[178:181], v[202:205], v[76:79]
	v_mfma_f32_16x16x32_bf16 v[68:71], v[170:173], v[214:217], v[68:71]
	v_mfma_f32_16x16x32_bf16 v[64:67], v[178:181], v[214:217], v[64:67]
	s_barrier
	s_add_i32 s2, s50, s40
	v_lshl_add_u64 v[206:207], s[30:31], 0, v[146:147]
	s_mov_b32 m0, s2
	ds_read_b128 v[182:185], v165 offset:16384
	ds_read_b128 v[186:189], v165 offset:17408
	ds_read_b128 v[190:193], v165 offset:18432
	ds_read_b128 v[194:197], v165 offset:19456
	ds_read_b128 v[198:201], v165 offset:20480
	ds_read_b128 v[202:205], v165 offset:21504
	ds_read_b128 v[210:213], v165 offset:22528
	ds_read_b128 v[214:217], v165 offset:23552
	global_load_lds_dwordx4 v[206:207], off
	s_add_i32 m0, s2, 0x2000
	s_add_u32 s62, s30, 0x160000
	v_lshl_add_u64 v[218:219], s[30:31], 0, v[150:151]
	s_addc_u32 s63, s31, 0
	s_add_i32 s2, s51, s40
	global_load_lds_dwordx4 v[218:219], off
	v_lshl_add_u64 v[220:221], s[62:63], 0, v[146:147]
	s_mov_b32 m0, s2
	v_lshl_add_u64 v[222:223], s[34:35], 0, v[148:149]
	global_load_lds_dwordx4 v[220:221], off
	v_lshl_add_u64 v[220:221], s[62:63], 0, v[150:151]
	s_add_i32 m0, s2, 0x2000
	s_nop 0
	global_load_lds_dwordx4 v[220:221], off
	v_lshl_add_u64 v[220:221], s[34:35], 0, v[144:145]
	s_mov_b32 m0, s41
	s_nop 0
	global_load_lds_dwordx4 v[220:221], off
	s_mov_b32 m0, s42
	s_nop 0
	global_load_lds_dwordx4 v[222:223], off
	s_waitcnt vmcnt(8)
	s_waitcnt lgkmcnt(0)
	s_barrier
; #define PG8_STAGE(bufoff, gbase, voff) do { _Pragma("unroll") for (int _i = 0; _i < 2; ++_i) \
;         __builtin_amdgcn_global_load_lds((const unsigned*)((const char*)(gbase) + (voff)[_i]), (LAS unsigned*)(lds + (bufoff) + ldsw + _i * 8192), 16, 0, 0); } while (0)
; #define PG8_LDA(dst, b, h) do { _Pragma("unroll") for (int m = 0; m < 4; ++m) _Pragma("unroll") for (int k = 0; k < 2; ++k) dst[m][k] = *(const LAS bf16x8*)(lds + PG8_SA(b, h) + aoff + m * 2048 + k * 1024); } while (0)
; #define PG8_LDB(dst, b, h) do { _Pragma("unroll") for (int n = 0; n < 2; ++n) _Pragma("unroll") for (int k = 0; k < 2; ++k) dst[n][k] = *(const LAS bf16x8*)(lds + PG8_SB(b, h) + boff + n * 2048 + k * 1024); } while (0)
; #define PG8_MMA(ai, bj, At, Bt) do { __builtin_amdgcn_s_setprio(1); _Pragma("unroll") for (int m = 0; m < 4; ++m) _Pragma("unroll") for (int n = 0; n < 2; ++n) _Pragma("unroll") for (int k = 0; k < 2; ++k) \
;         acc[ai][bj][m][n] = __builtin_amdgcn_mfma_f32_16x16x32_bf16(Bt[n][k], At[m][k], acc[ai][bj][m][n], 0, 0, 0); __builtin_amdgcn_s_setprio(0); } while (0)
; #define PG8_WAIT_V(n) asm volatile("s_waitcnt vmcnt(" #n ")" ::: "memory")
; #define PG8_WAIT_L(n) asm volatile("s_waitcnt lgkmcnt(" #n ")" ::: "memory")
; #define PG8_BAR __builtin_amdgcn_s_barrier()
; #define PG8_SCHED __builtin_amdgcn_sched_barrier(0)
; template <class Epi, class Sched>
; __device__ __forceinline__ void gemm_phase(LAS unsigned char* lds, const Gemm g, const Sched& S, const Epi& E) {
;     ...
;             PG8_WAIT_V(8); PG8_WAIT_L(0); PG8_BAR; PG8_MMA(1, 0, At, B0); PG8_MMA(1, 1, At, B1); PG8_BAR; PG8_SCHED;
;             PG8_LDB(B0, 1, 0); PG8_LDB(B1, 1, 1); PG8_SCHED; PG8_LDA(At, 1, 0); PG8_STAGE(PG8_SA(0, 1), a2 + hstepA, voffA);
;             PG8_WAIT_V(8); PG8_WAIT_L(0); PG8_BAR; PG8_MMA(0, 0, At, B0); PG8_MMA(0, 1, At, B1); PG8_BAR; PG8_SCHED;
;             PG8_LDA(At, 1, 1); PG8_STAGE(PG8_SB(1, 0), b3, voffB); PG8_STAGE(PG8_SB(1, 1), b3 + hstepB, voffB); PG8_STAGE(PG8_SA(1, 0), a3, voffA);
	s_waitcnt lgkmcnt(0)
	v_mfma_f32_16x16x32_bf16 v[60:63], v[128:131], v[182:185], v[60:63]
	v_mfma_f32_16x16x32_bf16 v[56:59], v[136:139], v[182:185], v[56:59]
	v_mfma_f32_16x16x32_bf16 v[52:55], v[128:131], v[190:193], v[52:55]
	v_mfma_f32_16x16x32_bf16 v[44:47], v[136:139], v[190:193], v[44:47]
	v_mfma_f32_16x16x32_bf16 v[36:39], v[128:131], v[198:201], v[36:39]
	v_mfma_f32_16x16x32_bf16 v[28:31], v[136:139], v[198:201], v[28:31]
	v_mfma_f32_16x16x32_bf16 v[20:23], v[128:131], v[210:213], v[20:23]
	v_mfma_f32_16x16x32_bf16 v[12:15], v[136:139], v[210:213], v[12:15]
	v_mfma_f32_16x16x32_bf16 v[60:63], v[132:135], v[186:189], v[60:63]
	v_mfma_f32_16x16x32_bf16 v[56:59], v[140:143], v[186:189], v[56:59]
	v_mfma_f32_16x16x32_bf16 v[52:55], v[132:135], v[194:197], v[52:55]
	v_mfma_f32_16x16x32_bf16 v[44:47], v[140:143], v[194:197], v[44:47]
	v_mfma_f32_16x16x32_bf16 v[36:39], v[132:135], v[202:205], v[36:39]
	v_mfma_f32_16x16x32_bf16 v[28:31], v[140:143], v[202:205], v[28:31]
	v_mfma_f32_16x16x32_bf16 v[20:23], v[132:135], v[214:217], v[20:23]
	v_mfma_f32_16x16x32_bf16 v[12:15], v[140:143], v[214:217], v[12:15]
	v_mfma_f32_16x16x32_bf16 v[48:51], v[166:169], v[182:185], v[48:51]
	v_mfma_f32_16x16x32_bf16 v[40:43], v[174:177], v[182:185], v[40:43]
	v_mfma_f32_16x16x32_bf16 v[32:35], v[166:169], v[190:193], v[32:35]
	v_mfma_f32_16x16x32_bf16 v[24:27], v[174:177], v[190:193], v[24:27]
	v_mfma_f32_16x16x32_bf16 v[16:19], v[166:169], v[198:201], v[16:19]
	v_mfma_f32_16x16x32_bf16 v[8:11], v[174:177], v[198:201], v[8:11]
	v_mfma_f32_16x16x32_bf16 v[4:7], v[166:169], v[210:213], v[4:7]
	v_mfma_f32_16x16x32_bf16 v[0:3], v[174:177], v[210:213], v[0:3]
	v_mfma_f32_16x16x32_bf16 v[48:51], v[170:173], v[186:189], v[48:51]
	v_mfma_f32_16x16x32_bf16 v[40:43], v[178:181], v[186:189], v[40:43]
	v_mfma_f32_16x16x32_bf16 v[32:35], v[170:173], v[194:197], v[32:35]
	v_mfma_f32_16x16x32_bf16 v[24:27], v[178:181], v[194:197], v[24:27]
	v_mfma_f32_16x16x32_bf16 v[16:19], v[170:173], v[202:205], v[16:19]
	v_mfma_f32_16x16x32_bf16 v[8:11], v[178:181], v[202:205], v[8:11]
	v_mfma_f32_16x16x32_bf16 v[4:7], v[170:173], v[214:217], v[4:7]
	v_mfma_f32_16x16x32_bf16 v[0:3], v[178:181], v[214:217], v[0:3]
	s_barrier
	s_add_i32 s2, 0, 0x18000
	s_add_i32 s62, 0, 0x1c000
	v_add_u32_e32 v140, s2, v161
	v_add_u32_e32 v178, s62, v161
	ds_read_b128 v[128:131], v140
	ds_read_b128 v[132:135], v140 offset:1024
	ds_read_b128 v[136:139], v140 offset:2048
	ds_read_b128 v[140:143], v140 offset:3072
	ds_read_b128 v[166:169], v178
	ds_read_b128 v[170:173], v178 offset:1024
	ds_read_b128 v[174:177], v178 offset:2048
	ds_read_b128 v[178:181], v178 offset:3072
	s_add_u32 s34, s34, 0x160000
	s_addc_u32 s35, s35, 0
	s_mov_b32 m0, s43
	v_lshl_add_u64 v[224:225], s[34:35], 0, v[144:145]
	ds_read_b128 v[182:185], v165 offset:32768
	ds_read_b128 v[186:189], v165 offset:33792
	ds_read_b128 v[190:193], v165 offset:34816
	ds_read_b128 v[194:197], v165 offset:35840
	ds_read_b128 v[198:201], v165 offset:36864
	ds_read_b128 v[202:205], v165 offset:37888
	ds_read_b128 v[210:213], v165 offset:38912
	ds_read_b128 v[214:217], v165 offset:39936
	global_load_lds_dwordx4 v[224:225], off
	v_lshl_add_u64 v[224:225], s[34:35], 0, v[148:149]
	s_mov_b32 m0, s44
	s_nop 0
	global_load_lds_dwordx4 v[224:225], off
	s_waitcnt vmcnt(8)
	s_waitcnt lgkmcnt(0)
	s_barrier
	s_waitcnt lgkmcnt(0)
	v_mfma_f32_16x16x32_bf16 v[124:127], v[128:131], v[182:185], v[124:127]
	v_mfma_f32_16x16x32_bf16 v[120:123], v[136:139], v[182:185], v[120:123]
	v_mfma_f32_16x16x32_bf16 v[116:119], v[128:131], v[190:193], v[116:119]
	v_mfma_f32_16x16x32_bf16 v[112:115], v[136:139], v[190:193], v[112:115]
	v_mfma_f32_16x16x32_bf16 v[108:111], v[128:131], v[198:201], v[108:111]
	v_mfma_f32_16x16x32_bf16 v[100:103], v[136:139], v[198:201], v[100:103]
	v_mfma_f32_16x16x32_bf16 v[92:95], v[128:131], v[210:213], v[92:95]
	v_mfma_f32_16x16x32_bf16 v[72:75], v[136:139], v[210:213], v[72:75]
	v_mfma_f32_16x16x32_bf16 v[124:127], v[132:135], v[186:189], v[124:127]
	v_mfma_f32_16x16x32_bf16 v[120:123], v[140:143], v[186:189], v[120:123]
	v_mfma_f32_16x16x32_bf16 v[116:119], v[132:135], v[194:197], v[116:119]
	v_mfma_f32_16x16x32_bf16 v[112:115], v[140:143], v[194:197], v[112:115]
	v_mfma_f32_16x16x32_bf16 v[108:111], v[132:135], v[202:205], v[108:111]
	v_mfma_f32_16x16x32_bf16 v[100:103], v[140:143], v[202:205], v[100:103]
	v_mfma_f32_16x16x32_bf16 v[92:95], v[132:135], v[214:217], v[92:95]
	v_mfma_f32_16x16x32_bf16 v[72:75], v[140:143], v[214:217], v[72:75]
	v_mfma_f32_16x16x32_bf16 v[104:107], v[166:169], v[182:185], v[104:107]
	v_mfma_f32_16x16x32_bf16 v[96:99], v[174:177], v[182:185], v[96:99]
	v_mfma_f32_16x16x32_bf16 v[88:91], v[166:169], v[190:193], v[88:91]
	v_mfma_f32_16x16x32_bf16 v[84:87], v[174:177], v[190:193], v[84:87]
	v_mfma_f32_16x16x32_bf16 v[80:83], v[166:169], v[198:201], v[80:83]
	v_mfma_f32_16x16x32_bf16 v[76:79], v[174:177], v[198:201], v[76:79]
	v_mfma_f32_16x16x32_bf16 v[68:71], v[166:169], v[210:213], v[68:71]
	v_mfma_f32_16x16x32_bf16 v[64:67], v[174:177], v[210:213], v[64:67]
	v_mfma_f32_16x16x32_bf16 v[104:107], v[170:173], v[186:189], v[104:107]
	v_mfma_f32_16x16x32_bf16 v[96:99], v[178:181], v[186:189], v[96:99]
	v_mfma_f32_16x16x32_bf16 v[88:91], v[170:173], v[194:197], v[88:91]
	v_mfma_f32_16x16x32_bf16 v[84:87], v[178:181], v[194:197], v[84:87]
	v_mfma_f32_16x16x32_bf16 v[80:83], v[170:173], v[202:205], v[80:83]
	v_mfma_f32_16x16x32_bf16 v[76:79], v[178:181], v[202:205], v[76:79]
	v_mfma_f32_16x16x32_bf16 v[68:71], v[170:173], v[214:217], v[68:71]
	v_mfma_f32_16x16x32_bf16 v[64:67], v[178:181], v[214:217], v[64:67]
	s_barrier
; #define PG8_STAGE(bufoff, gbase, voff) do { _Pragma("unroll") for (int _i = 0; _i < 2; ++_i) \
;         __builtin_amdgcn_global_load_lds((const unsigned*)((const char*)(gbase) + (voff)[_i]), (LAS unsigned*)(lds + (bufoff) + ldsw + _i * 8192), 16, 0, 0); } while (0)
; #define PG8_LDA(dst, b, h) do { _Pragma("unroll") for (int m = 0; m < 4; ++m) _Pragma("unroll") for (int k = 0; k < 2; ++k) dst[m][k] = *(const LAS bf16x8*)(lds + PG8_SA(b, h) + aoff + m * 2048 + k * 1024); } while (0)
; #define PG8_MMA(ai, bj, At, Bt) do { __builtin_amdgcn_s_setprio(1); _Pragma("unroll") for (int m = 0; m < 4; ++m) _Pragma("unroll") for (int n = 0; n < 2; ++n) _Pragma("unroll") for (int k = 0; k < 2; ++k) \
;         acc[ai][bj][m][n] = __builtin_amdgcn_mfma_f32_16x16x32_bf16(Bt[n][k], At[m][k], acc[ai][bj][m][n], 0, 0, 0); __builtin_amdgcn_s_setprio(0); } while (0)
; #define PG8_WAIT_V(n) asm volatile("s_waitcnt vmcnt(" #n ")" ::: "memory")
; #define PG8_WAIT_L(n) asm volatile("s_waitcnt lgkmcnt(" #n ")" ::: "memory")
; #define PG8_BAR __builtin_amdgcn_s_barrier()
; #define PG8_SCHED __builtin_amdgcn_sched_barrier(0)
; template <class Epi, class Sched>
; __device__ __forceinline__ void gemm_phase(LAS unsigned char* lds, const Gemm g, const Sched& S, const Epi& E) {
;     ...
;             PG8_LDA(At, 1, 1); PG8_STAGE(PG8_SB(1, 0), b3, voffB); PG8_STAGE(PG8_SB(1, 1), b3 + hstepB, voffB); PG8_STAGE(PG8_SA(1, 0), a3, voffA);
;             PG8_WAIT_V(8); PG8_WAIT_L(0); PG8_BAR; PG8_MMA(1, 0, At, B0); PG8_MMA(1, 1, At, B1); PG8_BAR; PG8_SCHED;
;         }
;         if (wr == 0) PG8_BAR;
	s_add_i32 s2, s2, s40
	v_lshl_add_u64 v[206:207], v[206:207], 0, s[14:15]
	s_mov_b32 m0, s2
	ds_read_b128 v[182:185], v165 offset:49152
	ds_read_b128 v[186:189], v165 offset:50176
	ds_read_b128 v[190:193], v165 offset:51200
	ds_read_b128 v[194:197], v165 offset:52224
	ds_read_b128 v[198:201], v165 offset:53248
	ds_read_b128 v[202:205], v165 offset:54272
	ds_read_b128 v[210:213], v165 offset:55296
	ds_read_b128 v[214:217], v165 offset:56320
	global_load_lds_dwordx4 v[206:207], off
	s_add_i32 m0, s2, 0x2000
	s_add_u32 s30, s30, 0x160080
	v_lshl_add_u64 v[206:207], v[218:219], 0, s[14:15]
	s_addc_u32 s31, s31, 0
	s_add_i32 s2, s62, s40
	global_load_lds_dwordx4 v[206:207], off
	v_lshl_add_u64 v[206:207], s[30:31], 0, v[146:147]
	s_mov_b32 m0, s2
	s_nop 0
	global_load_lds_dwordx4 v[206:207], off
	v_lshl_add_u64 v[206:207], s[30:31], 0, v[150:151]
	s_add_i32 m0, s2, 0x2000
	s_nop 0
	global_load_lds_dwordx4 v[206:207], off
	v_lshl_add_u64 v[206:207], v[220:221], 0, s[14:15]
	s_mov_b32 m0, s46
	s_nop 0
	global_load_lds_dwordx4 v[206:207], off
	v_lshl_add_u64 v[206:207], v[222:223], 0, s[14:15]
	s_mov_b32 m0, s47
	s_nop 0
	global_load_lds_dwordx4 v[206:207], off
	s_waitcnt vmcnt(8)
	s_waitcnt lgkmcnt(0)
	s_barrier
	s_waitcnt lgkmcnt(0)
	v_mfma_f32_16x16x32_bf16 v[60:63], v[128:131], v[182:185], v[60:63]
	v_mfma_f32_16x16x32_bf16 v[56:59], v[136:139], v[182:185], v[56:59]
	v_mfma_f32_16x16x32_bf16 v[52:55], v[128:131], v[190:193], v[52:55]
	v_mfma_f32_16x16x32_bf16 v[44:47], v[136:139], v[190:193], v[44:47]
	v_mfma_f32_16x16x32_bf16 v[36:39], v[128:131], v[198:201], v[36:39]
	v_mfma_f32_16x16x32_bf16 v[28:31], v[136:139], v[198:201], v[28:31]
	v_mfma_f32_16x16x32_bf16 v[20:23], v[128:131], v[210:213], v[20:23]
	v_mfma_f32_16x16x32_bf16 v[12:15], v[136:139], v[210:213], v[12:15]
	v_mfma_f32_16x16x32_bf16 v[60:63], v[132:135], v[186:189], v[60:63]
	v_mfma_f32_16x16x32_bf16 v[56:59], v[140:143], v[186:189], v[56:59]
	v_mfma_f32_16x16x32_bf16 v[52:55], v[132:135], v[194:197], v[52:55]
	v_mfma_f32_16x16x32_bf16 v[44:47], v[140:143], v[194:197], v[44:47]
	v_mfma_f32_16x16x32_bf16 v[36:39], v[132:135], v[202:205], v[36:39]
	v_mfma_f32_16x16x32_bf16 v[28:31], v[140:143], v[202:205], v[28:31]
	v_mfma_f32_16x16x32_bf16 v[20:23], v[132:135], v[214:217], v[20:23]
	v_mfma_f32_16x16x32_bf16 v[12:15], v[140:143], v[214:217], v[12:15]
	v_mfma_f32_16x16x32_bf16 v[48:51], v[166:169], v[182:185], v[48:51]
	v_mfma_f32_16x16x32_bf16 v[40:43], v[174:177], v[182:185], v[40:43]
	v_mfma_f32_16x16x32_bf16 v[32:35], v[166:169], v[190:193], v[32:35]
	v_mfma_f32_16x16x32_bf16 v[24:27], v[174:177], v[190:193], v[24:27]
	v_mfma_f32_16x16x32_bf16 v[16:19], v[166:169], v[198:201], v[16:19]
	v_mfma_f32_16x16x32_bf16 v[8:11], v[174:177], v[198:201], v[8:11]
	v_mfma_f32_16x16x32_bf16 v[4:7], v[166:169], v[210:213], v[4:7]
	v_mfma_f32_16x16x32_bf16 v[0:3], v[174:177], v[210:213], v[0:3]
	v_mfma_f32_16x16x32_bf16 v[48:51], v[170:173], v[186:189], v[48:51]
	v_mfma_f32_16x16x32_bf16 v[40:43], v[178:181], v[186:189], v[40:43]
	v_mfma_f32_16x16x32_bf16 v[32:35], v[170:173], v[194:197], v[32:35]
	v_mfma_f32_16x16x32_bf16 v[24:27], v[178:181], v[194:197], v[24:27]
	v_mfma_f32_16x16x32_bf16 v[16:19], v[170:173], v[202:205], v[16:19]
	v_mfma_f32_16x16x32_bf16 v[8:11], v[178:181], v[202:205], v[8:11]
	v_mfma_f32_16x16x32_bf16 v[4:7], v[170:173], v[214:217], v[4:7]
	v_mfma_f32_16x16x32_bf16 v[0:3], v[178:181], v[214:217], v[0:3]
	s_barrier
	s_add_i32 s61, s61, 2
	s_add_u32 s28, s28, 0x100
	s_addc_u32 s29, s29, 0
	s_add_u32 s33, s33, 0x100
	s_addc_u32 s60, s60, 0
	s_cmpk_gt_u32 s61, 0x55
	s_cbranch_scc0 .LBB0_1075
	s_and_b64 vcc, exec, s[16:17]
	s_cbranch_vccz .LBB0_1078
	s_barrier
